# route L0: final product-key merge with parallel LDS reads + in-place select tree
# speedup vs baseline: 1.0440x; 1.0030x over previous
.LBB0_625:
	s_and_saveexec_b64 s[4:5], s[12:13]
	s_cbranch_execz .LBB0_619
	v_or_b32_e32 v254, s46, v156
	v_lshlrev_b32_e32 v254, 9, v254
	v_lshl_or_b32 v254, s35, 6, v254
	ds_read_b32 v32, v133 offset:0
	ds_read_b32 v33, v133 offset:512
	ds_read_b32 v34, v133 offset:1024
	ds_read_b32 v35, v133 offset:1536
	ds_read_b32 v36, v133 offset:2048
	ds_read_b32 v37, v133 offset:2560
	ds_read_b32 v38, v133 offset:3072
	ds_read_b32 v39, v133 offset:3584
	ds_read_b32 v40, v133 offset:4096
	ds_read_b32 v41, v133 offset:4608
	ds_read_b32 v42, v133 offset:5120
	ds_read_b32 v43, v133 offset:5632
	ds_read_b32 v44, v133 offset:6144
	ds_read_b32 v45, v133 offset:6656
	ds_read_b32 v46, v133 offset:7168
	ds_read_b32 v47, v133 offset:7680
	v_mov_b32_e32 v48, 0
	v_mov_b32_e32 v49, 0
	v_bfe_u32 v0, v48, 0, 4
	v_bfe_u32 v1, v48, 4, 4
	v_bfe_u32 v2, v48, 8, 4
	v_bfe_u32 v3, v48, 12, 4
	v_bfe_u32 v4, v48, 16, 4
	v_bfe_u32 v5, v48, 20, 4
	v_bfe_u32 v6, v48, 24, 4
	v_bfe_u32 v7, v48, 28, 4
	v_bfe_u32 v8, v49, 0, 4
	v_bfe_u32 v9, v49, 4, 4
	v_bfe_u32 v10, v49, 8, 4
	v_bfe_u32 v11, v49, 12, 4
	v_bfe_u32 v12, v49, 16, 4
	v_bfe_u32 v13, v49, 20, 4
	v_bfe_u32 v14, v49, 24, 4
	v_bfe_u32 v15, v49, 28, 4
	v_lshl_add_u32 v0, v0, 9, v134
	v_lshl_add_u32 v1, v1, 9, v134
	v_lshl_add_u32 v2, v2, 9, v134
	v_lshl_add_u32 v3, v3, 9, v134
	v_lshl_add_u32 v4, v4, 9, v134
	v_lshl_add_u32 v5, v5, 9, v134
	v_lshl_add_u32 v6, v6, 9, v134
	v_lshl_add_u32 v7, v7, 9, v134
	v_lshl_add_u32 v8, v8, 9, v134
	v_lshl_add_u32 v9, v9, 9, v134
	v_lshl_add_u32 v10, v10, 9, v134
	v_lshl_add_u32 v11, v11, 9, v134
	v_lshl_add_u32 v12, v12, 9, v134
	v_lshl_add_u32 v13, v13, 9, v134
	v_lshl_add_u32 v14, v14, 9, v134
	v_lshl_add_u32 v15, v15, 9, v134
	ds_read_b32 v0, v0 offset:32768
	ds_read_b32 v1, v1 offset:32768
	ds_read_b32 v2, v2 offset:32768
	ds_read_b32 v3, v3 offset:32768
	ds_read_b32 v4, v4 offset:32768
	ds_read_b32 v5, v5 offset:32768
	ds_read_b32 v6, v6 offset:32768
	ds_read_b32 v7, v7 offset:32768
	ds_read_b32 v8, v8 offset:32768
	ds_read_b32 v9, v9 offset:32768
	ds_read_b32 v10, v10 offset:32768
	ds_read_b32 v11, v11 offset:32768
	ds_read_b32 v12, v12 offset:32768
	ds_read_b32 v13, v13 offset:32768
	ds_read_b32 v14, v14 offset:32768
	ds_read_b32 v15, v15 offset:32768
	s_waitcnt lgkmcnt(0)
	v_add_f32_e32 v0, v32, v0
	v_add_f32_e32 v1, v33, v1
	v_add_f32_e32 v2, v34, v2
	v_add_f32_e32 v3, v35, v3
	v_add_f32_e32 v4, v36, v4
	v_add_f32_e32 v5, v37, v5
	v_add_f32_e32 v6, v38, v6
	v_add_f32_e32 v7, v39, v7
	v_add_f32_e32 v8, v40, v8
	v_add_f32_e32 v9, v41, v9
	v_add_f32_e32 v10, v42, v10
	v_add_f32_e32 v11, v43, v11
	v_add_f32_e32 v12, v44, v12
	v_add_f32_e32 v13, v45, v13
	v_add_f32_e32 v14, v46, v14
	v_add_f32_e32 v15, v47, v15
	v_cmp_gt_f32_e32 vcc, v1, v0
	v_cmp_gt_f32_e64 s[8:9], v3, v2
	v_cmp_gt_f32_e64 s[98:99], v5, v4
	v_cmp_gt_f32_e64 s[100:101], v7, v6
	v_cndmask_b32_e64 v0, v0, v1, vcc
	v_cndmask_b32_e64 v1, 0, 1, vcc
	v_cndmask_b32_e64 v2, v2, v3, s[8:9]
	v_cndmask_b32_e64 v3, 2, 3, s[8:9]
	v_cndmask_b32_e64 v4, v4, v5, s[98:99]
	v_cndmask_b32_e64 v5, 4, 5, s[98:99]
	v_cndmask_b32_e64 v6, v6, v7, s[100:101]
	v_cndmask_b32_e64 v7, 6, 7, s[100:101]
	v_cmp_gt_f32_e32 vcc, v9, v8
	v_cmp_gt_f32_e64 s[8:9], v11, v10
	v_cmp_gt_f32_e64 s[98:99], v13, v12
	v_cmp_gt_f32_e64 s[100:101], v15, v14
	v_cndmask_b32_e64 v8, v8, v9, vcc
	v_cndmask_b32_e64 v9, 8, 9, vcc
	v_cndmask_b32_e64 v10, v10, v11, s[8:9]
	v_cndmask_b32_e64 v11, 10, 11, s[8:9]
	v_cndmask_b32_e64 v12, v12, v13, s[98:99]
	v_cndmask_b32_e64 v13, 12, 13, s[98:99]
	v_cndmask_b32_e64 v14, v14, v15, s[100:101]
	v_cndmask_b32_e64 v15, 14, 15, s[100:101]
	v_cmp_gt_f32_e32 vcc, v2, v0
	v_cmp_gt_f32_e64 s[8:9], v6, v4
	v_cmp_gt_f32_e64 s[98:99], v10, v8
	v_cmp_gt_f32_e64 s[100:101], v14, v12
	v_cndmask_b32_e64 v0, v0, v2, vcc
	v_cndmask_b32_e64 v1, v1, v3, vcc
	v_cndmask_b32_e64 v4, v4, v6, s[8:9]
	v_cndmask_b32_e64 v5, v5, v7, s[8:9]
	v_cndmask_b32_e64 v8, v8, v10, s[98:99]
	v_cndmask_b32_e64 v9, v9, v11, s[98:99]
	v_cndmask_b32_e64 v12, v12, v14, s[100:101]
	v_cndmask_b32_e64 v13, v13, v15, s[100:101]
	v_cmp_gt_f32_e32 vcc, v4, v0
	v_cmp_gt_f32_e64 s[8:9], v12, v8
	s_nop 0
	v_cndmask_b32_e64 v0, v0, v4, vcc
	v_cndmask_b32_e64 v1, v1, v5, vcc
	v_cndmask_b32_e64 v8, v8, v12, s[8:9]
	v_cndmask_b32_e64 v9, v9, v13, s[8:9]
	v_cmp_gt_f32_e32 vcc, v8, v0
	s_nop 1
	v_cndmask_b32_e64 v0, v0, v8, vcc
	v_cndmask_b32_e64 v1, v1, v9, vcc
	v_mov_b32_e32 v255, v0
	v_mov_b32_e32 v16, 1.0
	v_lshlrev_b32_e32 v50, 2, v1
	v_lshrrev_b64 v[52:53], v50, v[48:49]
	v_lshl_add_u32 v51, v1, 7, v135
	v_and_b32_e32 v52, 15, v52
	v_lshl_add_u32 v52, v52, 7, v206
	ds_read_u8 v53, v51
	ds_read_u8 v54, v52 offset:40960
	v_lshlrev_b64 v[50:51], v50, 1
	v_lshl_add_u64 v[48:49], v[50:51], 0, v[48:49]
	v_bfe_u32 v0, v48, 0, 4
	v_bfe_u32 v1, v48, 4, 4
	v_bfe_u32 v2, v48, 8, 4
	v_bfe_u32 v3, v48, 12, 4
	v_bfe_u32 v4, v48, 16, 4
	v_bfe_u32 v5, v48, 20, 4
	v_bfe_u32 v6, v48, 24, 4
	v_bfe_u32 v7, v48, 28, 4
	v_bfe_u32 v8, v49, 0, 4
	v_bfe_u32 v9, v49, 4, 4
	v_bfe_u32 v10, v49, 8, 4
	v_bfe_u32 v11, v49, 12, 4
	v_bfe_u32 v12, v49, 16, 4
	v_bfe_u32 v13, v49, 20, 4
	v_bfe_u32 v14, v49, 24, 4
	v_bfe_u32 v15, v49, 28, 4
	v_lshl_add_u32 v0, v0, 9, v134
	v_lshl_add_u32 v1, v1, 9, v134
	v_lshl_add_u32 v2, v2, 9, v134
	v_lshl_add_u32 v3, v3, 9, v134
	v_lshl_add_u32 v4, v4, 9, v134
	v_lshl_add_u32 v5, v5, 9, v134
	v_lshl_add_u32 v6, v6, 9, v134
	v_lshl_add_u32 v7, v7, 9, v134
	v_lshl_add_u32 v8, v8, 9, v134
	v_lshl_add_u32 v9, v9, 9, v134
	v_lshl_add_u32 v10, v10, 9, v134
	v_lshl_add_u32 v11, v11, 9, v134
	v_lshl_add_u32 v12, v12, 9, v134
	v_lshl_add_u32 v13, v13, 9, v134
	v_lshl_add_u32 v14, v14, 9, v134
	v_lshl_add_u32 v15, v15, 9, v134
	s_waitcnt lgkmcnt(0)
	v_lshl_add_u32 v53, v53, 7, v54
	global_store_dword v254, v53, s[38:39] offset:0
	ds_read_b32 v0, v0 offset:32768
	ds_read_b32 v1, v1 offset:32768
	ds_read_b32 v2, v2 offset:32768
	ds_read_b32 v3, v3 offset:32768
	ds_read_b32 v4, v4 offset:32768
	ds_read_b32 v5, v5 offset:32768
	ds_read_b32 v6, v6 offset:32768
	ds_read_b32 v7, v7 offset:32768
	ds_read_b32 v8, v8 offset:32768
	ds_read_b32 v9, v9 offset:32768
	ds_read_b32 v10, v10 offset:32768
	ds_read_b32 v11, v11 offset:32768
	ds_read_b32 v12, v12 offset:32768
	ds_read_b32 v13, v13 offset:32768
	ds_read_b32 v14, v14 offset:32768
	ds_read_b32 v15, v15 offset:32768
	s_waitcnt lgkmcnt(0)
	v_add_f32_e32 v0, v32, v0
	v_add_f32_e32 v1, v33, v1
	v_add_f32_e32 v2, v34, v2
	v_add_f32_e32 v3, v35, v3
	v_add_f32_e32 v4, v36, v4
	v_add_f32_e32 v5, v37, v5
	v_add_f32_e32 v6, v38, v6
	v_add_f32_e32 v7, v39, v7
	v_add_f32_e32 v8, v40, v8
	v_add_f32_e32 v9, v41, v9
	v_add_f32_e32 v10, v42, v10
	v_add_f32_e32 v11, v43, v11
	v_add_f32_e32 v12, v44, v12
	v_add_f32_e32 v13, v45, v13
	v_add_f32_e32 v14, v46, v14
	v_add_f32_e32 v15, v47, v15
	v_cmp_gt_f32_e32 vcc, v1, v0
	v_cmp_gt_f32_e64 s[8:9], v3, v2
	v_cmp_gt_f32_e64 s[98:99], v5, v4
	v_cmp_gt_f32_e64 s[100:101], v7, v6
	v_cndmask_b32_e64 v0, v0, v1, vcc
	v_cndmask_b32_e64 v1, 0, 1, vcc
	v_cndmask_b32_e64 v2, v2, v3, s[8:9]
	v_cndmask_b32_e64 v3, 2, 3, s[8:9]
	v_cndmask_b32_e64 v4, v4, v5, s[98:99]
	v_cndmask_b32_e64 v5, 4, 5, s[98:99]
	v_cndmask_b32_e64 v6, v6, v7, s[100:101]
	v_cndmask_b32_e64 v7, 6, 7, s[100:101]
	v_cmp_gt_f32_e32 vcc, v9, v8
	v_cmp_gt_f32_e64 s[8:9], v11, v10
	v_cmp_gt_f32_e64 s[98:99], v13, v12
	v_cmp_gt_f32_e64 s[100:101], v15, v14
	v_cndmask_b32_e64 v8, v8, v9, vcc
	v_cndmask_b32_e64 v9, 8, 9, vcc
	v_cndmask_b32_e64 v10, v10, v11, s[8:9]
	v_cndmask_b32_e64 v11, 10, 11, s[8:9]
	v_cndmask_b32_e64 v12, v12, v13, s[98:99]
	v_cndmask_b32_e64 v13, 12, 13, s[98:99]
	v_cndmask_b32_e64 v14, v14, v15, s[100:101]
	v_cndmask_b32_e64 v15, 14, 15, s[100:101]
	v_cmp_gt_f32_e32 vcc, v2, v0
	v_cmp_gt_f32_e64 s[8:9], v6, v4
	v_cmp_gt_f32_e64 s[98:99], v10, v8
	v_cmp_gt_f32_e64 s[100:101], v14, v12
	v_cndmask_b32_e64 v0, v0, v2, vcc
	v_cndmask_b32_e64 v1, v1, v3, vcc
	v_cndmask_b32_e64 v4, v4, v6, s[8:9]
	v_cndmask_b32_e64 v5, v5, v7, s[8:9]
	v_cndmask_b32_e64 v8, v8, v10, s[98:99]
	v_cndmask_b32_e64 v9, v9, v11, s[98:99]
	v_cndmask_b32_e64 v12, v12, v14, s[100:101]
	v_cndmask_b32_e64 v13, v13, v15, s[100:101]
	v_cmp_gt_f32_e32 vcc, v4, v0
	v_cmp_gt_f32_e64 s[8:9], v12, v8
	s_nop 0
	v_cndmask_b32_e64 v0, v0, v4, vcc
	v_cndmask_b32_e64 v1, v1, v5, vcc
	v_cndmask_b32_e64 v8, v8, v12, s[8:9]
	v_cndmask_b32_e64 v9, v9, v13, s[8:9]
	v_cmp_gt_f32_e32 vcc, v8, v0
	s_nop 1
	v_cndmask_b32_e64 v0, v0, v8, vcc
	v_cndmask_b32_e64 v1, v1, v9, vcc
	v_sub_f32_e32 v17, v0, v255
	v_mul_f32_e32 v17, 0x3fb8aa3b, v17
	v_exp_f32_e32 v17, v17
	v_lshlrev_b32_e32 v50, 2, v1
	v_lshrrev_b64 v[52:53], v50, v[48:49]
	v_lshl_add_u32 v51, v1, 7, v135
	v_and_b32_e32 v52, 15, v52
	v_lshl_add_u32 v52, v52, 7, v206
	ds_read_u8 v53, v51
	ds_read_u8 v54, v52 offset:40960
	v_lshlrev_b64 v[50:51], v50, 1
	v_lshl_add_u64 v[48:49], v[50:51], 0, v[48:49]
	v_bfe_u32 v0, v48, 0, 4
	v_bfe_u32 v1, v48, 4, 4
	v_bfe_u32 v2, v48, 8, 4
	v_bfe_u32 v3, v48, 12, 4
	v_bfe_u32 v4, v48, 16, 4
	v_bfe_u32 v5, v48, 20, 4
	v_bfe_u32 v6, v48, 24, 4
	v_bfe_u32 v7, v48, 28, 4
	v_bfe_u32 v8, v49, 0, 4
	v_bfe_u32 v9, v49, 4, 4
	v_bfe_u32 v10, v49, 8, 4
	v_bfe_u32 v11, v49, 12, 4
	v_bfe_u32 v12, v49, 16, 4
	v_bfe_u32 v13, v49, 20, 4
	v_bfe_u32 v14, v49, 24, 4
	v_bfe_u32 v15, v49, 28, 4
	v_lshl_add_u32 v0, v0, 9, v134
	v_lshl_add_u32 v1, v1, 9, v134
	v_lshl_add_u32 v2, v2, 9, v134
	v_lshl_add_u32 v3, v3, 9, v134
	v_lshl_add_u32 v4, v4, 9, v134
	v_lshl_add_u32 v5, v5, 9, v134
	v_lshl_add_u32 v6, v6, 9, v134
	v_lshl_add_u32 v7, v7, 9, v134
	v_lshl_add_u32 v8, v8, 9, v134
	v_lshl_add_u32 v9, v9, 9, v134
	v_lshl_add_u32 v10, v10, 9, v134
	v_lshl_add_u32 v11, v11, 9, v134
	v_lshl_add_u32 v12, v12, 9, v134
	v_lshl_add_u32 v13, v13, 9, v134
	v_lshl_add_u32 v14, v14, 9, v134
	v_lshl_add_u32 v15, v15, 9, v134
	s_waitcnt lgkmcnt(0)
	v_lshl_add_u32 v53, v53, 7, v54
	global_store_dword v254, v53, s[38:39] offset:4
	ds_read_b32 v0, v0 offset:32768
	ds_read_b32 v1, v1 offset:32768
	ds_read_b32 v2, v2 offset:32768
	ds_read_b32 v3, v3 offset:32768
	ds_read_b32 v4, v4 offset:32768
	ds_read_b32 v5, v5 offset:32768
	ds_read_b32 v6, v6 offset:32768
	ds_read_b32 v7, v7 offset:32768
	ds_read_b32 v8, v8 offset:32768
	ds_read_b32 v9, v9 offset:32768
	ds_read_b32 v10, v10 offset:32768
	ds_read_b32 v11, v11 offset:32768
	ds_read_b32 v12, v12 offset:32768
	ds_read_b32 v13, v13 offset:32768
	ds_read_b32 v14, v14 offset:32768
	ds_read_b32 v15, v15 offset:32768
	s_waitcnt lgkmcnt(0)
	v_add_f32_e32 v0, v32, v0
	v_add_f32_e32 v1, v33, v1
	v_add_f32_e32 v2, v34, v2
	v_add_f32_e32 v3, v35, v3
	v_add_f32_e32 v4, v36, v4
	v_add_f32_e32 v5, v37, v5
	v_add_f32_e32 v6, v38, v6
	v_add_f32_e32 v7, v39, v7
	v_add_f32_e32 v8, v40, v8
	v_add_f32_e32 v9, v41, v9
	v_add_f32_e32 v10, v42, v10
	v_add_f32_e32 v11, v43, v11
	v_add_f32_e32 v12, v44, v12
	v_add_f32_e32 v13, v45, v13
	v_add_f32_e32 v14, v46, v14
	v_add_f32_e32 v15, v47, v15
	v_cmp_gt_f32_e32 vcc, v1, v0
	v_cmp_gt_f32_e64 s[8:9], v3, v2
	v_cmp_gt_f32_e64 s[98:99], v5, v4
	v_cmp_gt_f32_e64 s[100:101], v7, v6
	v_cndmask_b32_e64 v0, v0, v1, vcc
	v_cndmask_b32_e64 v1, 0, 1, vcc
	v_cndmask_b32_e64 v2, v2, v3, s[8:9]
	v_cndmask_b32_e64 v3, 2, 3, s[8:9]
	v_cndmask_b32_e64 v4, v4, v5, s[98:99]
	v_cndmask_b32_e64 v5, 4, 5, s[98:99]
	v_cndmask_b32_e64 v6, v6, v7, s[100:101]
	v_cndmask_b32_e64 v7, 6, 7, s[100:101]
	v_cmp_gt_f32_e32 vcc, v9, v8
	v_cmp_gt_f32_e64 s[8:9], v11, v10
	v_cmp_gt_f32_e64 s[98:99], v13, v12
	v_cmp_gt_f32_e64 s[100:101], v15, v14
	v_cndmask_b32_e64 v8, v8, v9, vcc
	v_cndmask_b32_e64 v9, 8, 9, vcc
	v_cndmask_b32_e64 v10, v10, v11, s[8:9]
	v_cndmask_b32_e64 v11, 10, 11, s[8:9]
	v_cndmask_b32_e64 v12, v12, v13, s[98:99]
	v_cndmask_b32_e64 v13, 12, 13, s[98:99]
	v_cndmask_b32_e64 v14, v14, v15, s[100:101]
	v_cndmask_b32_e64 v15, 14, 15, s[100:101]
	v_cmp_gt_f32_e32 vcc, v2, v0
	v_cmp_gt_f32_e64 s[8:9], v6, v4
	v_cmp_gt_f32_e64 s[98:99], v10, v8
	v_cmp_gt_f32_e64 s[100:101], v14, v12
	v_cndmask_b32_e64 v0, v0, v2, vcc
	v_cndmask_b32_e64 v1, v1, v3, vcc
	v_cndmask_b32_e64 v4, v4, v6, s[8:9]
	v_cndmask_b32_e64 v5, v5, v7, s[8:9]
	v_cndmask_b32_e64 v8, v8, v10, s[98:99]
	v_cndmask_b32_e64 v9, v9, v11, s[98:99]
	v_cndmask_b32_e64 v12, v12, v14, s[100:101]
	v_cndmask_b32_e64 v13, v13, v15, s[100:101]
	v_cmp_gt_f32_e32 vcc, v4, v0
	v_cmp_gt_f32_e64 s[8:9], v12, v8
	s_nop 0
	v_cndmask_b32_e64 v0, v0, v4, vcc
	v_cndmask_b32_e64 v1, v1, v5, vcc
	v_cndmask_b32_e64 v8, v8, v12, s[8:9]
	v_cndmask_b32_e64 v9, v9, v13, s[8:9]
	v_cmp_gt_f32_e32 vcc, v8, v0
	s_nop 1
	v_cndmask_b32_e64 v0, v0, v8, vcc
	v_cndmask_b32_e64 v1, v1, v9, vcc
	v_sub_f32_e32 v18, v0, v255
	v_mul_f32_e32 v18, 0x3fb8aa3b, v18
	v_exp_f32_e32 v18, v18
	v_lshlrev_b32_e32 v50, 2, v1
	v_lshrrev_b64 v[52:53], v50, v[48:49]
	v_lshl_add_u32 v51, v1, 7, v135
	v_and_b32_e32 v52, 15, v52
	v_lshl_add_u32 v52, v52, 7, v206
	ds_read_u8 v53, v51
	ds_read_u8 v54, v52 offset:40960
	v_lshlrev_b64 v[50:51], v50, 1
	v_lshl_add_u64 v[48:49], v[50:51], 0, v[48:49]
	v_bfe_u32 v0, v48, 0, 4
	v_bfe_u32 v1, v48, 4, 4
	v_bfe_u32 v2, v48, 8, 4
	v_bfe_u32 v3, v48, 12, 4
	v_bfe_u32 v4, v48, 16, 4
	v_bfe_u32 v5, v48, 20, 4
	v_bfe_u32 v6, v48, 24, 4
	v_bfe_u32 v7, v48, 28, 4
	v_bfe_u32 v8, v49, 0, 4
	v_bfe_u32 v9, v49, 4, 4
	v_bfe_u32 v10, v49, 8, 4
	v_bfe_u32 v11, v49, 12, 4
	v_bfe_u32 v12, v49, 16, 4
	v_bfe_u32 v13, v49, 20, 4
	v_bfe_u32 v14, v49, 24, 4
	v_bfe_u32 v15, v49, 28, 4
	v_lshl_add_u32 v0, v0, 9, v134
	v_lshl_add_u32 v1, v1, 9, v134
	v_lshl_add_u32 v2, v2, 9, v134
	v_lshl_add_u32 v3, v3, 9, v134
	v_lshl_add_u32 v4, v4, 9, v134
	v_lshl_add_u32 v5, v5, 9, v134
	v_lshl_add_u32 v6, v6, 9, v134
	v_lshl_add_u32 v7, v7, 9, v134
	v_lshl_add_u32 v8, v8, 9, v134
	v_lshl_add_u32 v9, v9, 9, v134
	v_lshl_add_u32 v10, v10, 9, v134
	v_lshl_add_u32 v11, v11, 9, v134
	v_lshl_add_u32 v12, v12, 9, v134
	v_lshl_add_u32 v13, v13, 9, v134
	v_lshl_add_u32 v14, v14, 9, v134
	v_lshl_add_u32 v15, v15, 9, v134
	s_waitcnt lgkmcnt(0)
	v_lshl_add_u32 v53, v53, 7, v54
	global_store_dword v254, v53, s[38:39] offset:8
	ds_read_b32 v0, v0 offset:32768
	ds_read_b32 v1, v1 offset:32768
	ds_read_b32 v2, v2 offset:32768
	ds_read_b32 v3, v3 offset:32768
	ds_read_b32 v4, v4 offset:32768
	ds_read_b32 v5, v5 offset:32768
	ds_read_b32 v6, v6 offset:32768
	ds_read_b32 v7, v7 offset:32768
	ds_read_b32 v8, v8 offset:32768
	ds_read_b32 v9, v9 offset:32768
	ds_read_b32 v10, v10 offset:32768
	ds_read_b32 v11, v11 offset:32768
	ds_read_b32 v12, v12 offset:32768
	ds_read_b32 v13, v13 offset:32768
	ds_read_b32 v14, v14 offset:32768
	ds_read_b32 v15, v15 offset:32768
	s_waitcnt lgkmcnt(0)
	v_add_f32_e32 v0, v32, v0
	v_add_f32_e32 v1, v33, v1
	v_add_f32_e32 v2, v34, v2
	v_add_f32_e32 v3, v35, v3
	v_add_f32_e32 v4, v36, v4
	v_add_f32_e32 v5, v37, v5
	v_add_f32_e32 v6, v38, v6
	v_add_f32_e32 v7, v39, v7
	v_add_f32_e32 v8, v40, v8
	v_add_f32_e32 v9, v41, v9
	v_add_f32_e32 v10, v42, v10
	v_add_f32_e32 v11, v43, v11
	v_add_f32_e32 v12, v44, v12
	v_add_f32_e32 v13, v45, v13
	v_add_f32_e32 v14, v46, v14
	v_add_f32_e32 v15, v47, v15
	v_cmp_gt_f32_e32 vcc, v1, v0
	v_cmp_gt_f32_e64 s[8:9], v3, v2
	v_cmp_gt_f32_e64 s[98:99], v5, v4
	v_cmp_gt_f32_e64 s[100:101], v7, v6
	v_cndmask_b32_e64 v0, v0, v1, vcc
	v_cndmask_b32_e64 v1, 0, 1, vcc
	v_cndmask_b32_e64 v2, v2, v3, s[8:9]
	v_cndmask_b32_e64 v3, 2, 3, s[8:9]
	v_cndmask_b32_e64 v4, v4, v5, s[98:99]
	v_cndmask_b32_e64 v5, 4, 5, s[98:99]
	v_cndmask_b32_e64 v6, v6, v7, s[100:101]
	v_cndmask_b32_e64 v7, 6, 7, s[100:101]
	v_cmp_gt_f32_e32 vcc, v9, v8
	v_cmp_gt_f32_e64 s[8:9], v11, v10
	v_cmp_gt_f32_e64 s[98:99], v13, v12
	v_cmp_gt_f32_e64 s[100:101], v15, v14
	v_cndmask_b32_e64 v8, v8, v9, vcc
	v_cndmask_b32_e64 v9, 8, 9, vcc
	v_cndmask_b32_e64 v10, v10, v11, s[8:9]
	v_cndmask_b32_e64 v11, 10, 11, s[8:9]
	v_cndmask_b32_e64 v12, v12, v13, s[98:99]
	v_cndmask_b32_e64 v13, 12, 13, s[98:99]
	v_cndmask_b32_e64 v14, v14, v15, s[100:101]
	v_cndmask_b32_e64 v15, 14, 15, s[100:101]
	v_cmp_gt_f32_e32 vcc, v2, v0
	v_cmp_gt_f32_e64 s[8:9], v6, v4
	v_cmp_gt_f32_e64 s[98:99], v10, v8
	v_cmp_gt_f32_e64 s[100:101], v14, v12
	v_cndmask_b32_e64 v0, v0, v2, vcc
	v_cndmask_b32_e64 v1, v1, v3, vcc
	v_cndmask_b32_e64 v4, v4, v6, s[8:9]
	v_cndmask_b32_e64 v5, v5, v7, s[8:9]
	v_cndmask_b32_e64 v8, v8, v10, s[98:99]
	v_cndmask_b32_e64 v9, v9, v11, s[98:99]
	v_cndmask_b32_e64 v12, v12, v14, s[100:101]
	v_cndmask_b32_e64 v13, v13, v15, s[100:101]
	v_cmp_gt_f32_e32 vcc, v4, v0
	v_cmp_gt_f32_e64 s[8:9], v12, v8
	s_nop 0
	v_cndmask_b32_e64 v0, v0, v4, vcc
	v_cndmask_b32_e64 v1, v1, v5, vcc
	v_cndmask_b32_e64 v8, v8, v12, s[8:9]
	v_cndmask_b32_e64 v9, v9, v13, s[8:9]
	v_cmp_gt_f32_e32 vcc, v8, v0
	s_nop 1
	v_cndmask_b32_e64 v0, v0, v8, vcc
	v_cndmask_b32_e64 v1, v1, v9, vcc
	v_sub_f32_e32 v19, v0, v255
	v_mul_f32_e32 v19, 0x3fb8aa3b, v19
	v_exp_f32_e32 v19, v19
	v_lshlrev_b32_e32 v50, 2, v1
	v_lshrrev_b64 v[52:53], v50, v[48:49]
	v_lshl_add_u32 v51, v1, 7, v135
	v_and_b32_e32 v52, 15, v52
	v_lshl_add_u32 v52, v52, 7, v206
	ds_read_u8 v53, v51
	ds_read_u8 v54, v52 offset:40960
	v_lshlrev_b64 v[50:51], v50, 1
	v_lshl_add_u64 v[48:49], v[50:51], 0, v[48:49]
	v_bfe_u32 v0, v48, 0, 4
	v_bfe_u32 v1, v48, 4, 4
	v_bfe_u32 v2, v48, 8, 4
	v_bfe_u32 v3, v48, 12, 4
	v_bfe_u32 v4, v48, 16, 4
	v_bfe_u32 v5, v48, 20, 4
	v_bfe_u32 v6, v48, 24, 4
	v_bfe_u32 v7, v48, 28, 4
	v_bfe_u32 v8, v49, 0, 4
	v_bfe_u32 v9, v49, 4, 4
	v_bfe_u32 v10, v49, 8, 4
	v_bfe_u32 v11, v49, 12, 4
	v_bfe_u32 v12, v49, 16, 4
	v_bfe_u32 v13, v49, 20, 4
	v_bfe_u32 v14, v49, 24, 4
	v_bfe_u32 v15, v49, 28, 4
	v_lshl_add_u32 v0, v0, 9, v134
	v_lshl_add_u32 v1, v1, 9, v134
	v_lshl_add_u32 v2, v2, 9, v134
	v_lshl_add_u32 v3, v3, 9, v134
	v_lshl_add_u32 v4, v4, 9, v134
	v_lshl_add_u32 v5, v5, 9, v134
	v_lshl_add_u32 v6, v6, 9, v134
	v_lshl_add_u32 v7, v7, 9, v134
	v_lshl_add_u32 v8, v8, 9, v134
	v_lshl_add_u32 v9, v9, 9, v134
	v_lshl_add_u32 v10, v10, 9, v134
	v_lshl_add_u32 v11, v11, 9, v134
	v_lshl_add_u32 v12, v12, 9, v134
	v_lshl_add_u32 v13, v13, 9, v134
	v_lshl_add_u32 v14, v14, 9, v134
	v_lshl_add_u32 v15, v15, 9, v134
	s_waitcnt lgkmcnt(0)
	v_lshl_add_u32 v53, v53, 7, v54
	global_store_dword v254, v53, s[38:39] offset:12
	ds_read_b32 v0, v0 offset:32768
	ds_read_b32 v1, v1 offset:32768
	ds_read_b32 v2, v2 offset:32768
	ds_read_b32 v3, v3 offset:32768
	ds_read_b32 v4, v4 offset:32768
	ds_read_b32 v5, v5 offset:32768
	ds_read_b32 v6, v6 offset:32768
	ds_read_b32 v7, v7 offset:32768
	ds_read_b32 v8, v8 offset:32768
	ds_read_b32 v9, v9 offset:32768
	ds_read_b32 v10, v10 offset:32768
	ds_read_b32 v11, v11 offset:32768
	ds_read_b32 v12, v12 offset:32768
	ds_read_b32 v13, v13 offset:32768
	ds_read_b32 v14, v14 offset:32768
	ds_read_b32 v15, v15 offset:32768
	s_waitcnt lgkmcnt(0)
	v_add_f32_e32 v0, v32, v0
	v_add_f32_e32 v1, v33, v1
	v_add_f32_e32 v2, v34, v2
	v_add_f32_e32 v3, v35, v3
	v_add_f32_e32 v4, v36, v4
	v_add_f32_e32 v5, v37, v5
	v_add_f32_e32 v6, v38, v6
	v_add_f32_e32 v7, v39, v7
	v_add_f32_e32 v8, v40, v8
	v_add_f32_e32 v9, v41, v9
	v_add_f32_e32 v10, v42, v10
	v_add_f32_e32 v11, v43, v11
	v_add_f32_e32 v12, v44, v12
	v_add_f32_e32 v13, v45, v13
	v_add_f32_e32 v14, v46, v14
	v_add_f32_e32 v15, v47, v15
	v_cmp_gt_f32_e32 vcc, v1, v0
	v_cmp_gt_f32_e64 s[8:9], v3, v2
	v_cmp_gt_f32_e64 s[98:99], v5, v4
	v_cmp_gt_f32_e64 s[100:101], v7, v6
	v_cndmask_b32_e64 v0, v0, v1, vcc
	v_cndmask_b32_e64 v1, 0, 1, vcc
	v_cndmask_b32_e64 v2, v2, v3, s[8:9]
	v_cndmask_b32_e64 v3, 2, 3, s[8:9]
	v_cndmask_b32_e64 v4, v4, v5, s[98:99]
	v_cndmask_b32_e64 v5, 4, 5, s[98:99]
	v_cndmask_b32_e64 v6, v6, v7, s[100:101]
	v_cndmask_b32_e64 v7, 6, 7, s[100:101]
	v_cmp_gt_f32_e32 vcc, v9, v8
	v_cmp_gt_f32_e64 s[8:9], v11, v10
	v_cmp_gt_f32_e64 s[98:99], v13, v12
	v_cmp_gt_f32_e64 s[100:101], v15, v14
	v_cndmask_b32_e64 v8, v8, v9, vcc
	v_cndmask_b32_e64 v9, 8, 9, vcc
	v_cndmask_b32_e64 v10, v10, v11, s[8:9]
	v_cndmask_b32_e64 v11, 10, 11, s[8:9]
	v_cndmask_b32_e64 v12, v12, v13, s[98:99]
	v_cndmask_b32_e64 v13, 12, 13, s[98:99]
	v_cndmask_b32_e64 v14, v14, v15, s[100:101]
	v_cndmask_b32_e64 v15, 14, 15, s[100:101]
	v_cmp_gt_f32_e32 vcc, v2, v0
	v_cmp_gt_f32_e64 s[8:9], v6, v4
	v_cmp_gt_f32_e64 s[98:99], v10, v8
	v_cmp_gt_f32_e64 s[100:101], v14, v12
	v_cndmask_b32_e64 v0, v0, v2, vcc
	v_cndmask_b32_e64 v1, v1, v3, vcc
	v_cndmask_b32_e64 v4, v4, v6, s[8:9]
	v_cndmask_b32_e64 v5, v5, v7, s[8:9]
	v_cndmask_b32_e64 v8, v8, v10, s[98:99]
	v_cndmask_b32_e64 v9, v9, v11, s[98:99]
	v_cndmask_b32_e64 v12, v12, v14, s[100:101]
	v_cndmask_b32_e64 v13, v13, v15, s[100:101]
	v_cmp_gt_f32_e32 vcc, v4, v0
	v_cmp_gt_f32_e64 s[8:9], v12, v8
	s_nop 0
	v_cndmask_b32_e64 v0, v0, v4, vcc
	v_cndmask_b32_e64 v1, v1, v5, vcc
	v_cndmask_b32_e64 v8, v8, v12, s[8:9]
	v_cndmask_b32_e64 v9, v9, v13, s[8:9]
	v_cmp_gt_f32_e32 vcc, v8, v0
	s_nop 1
	v_cndmask_b32_e64 v0, v0, v8, vcc
	v_cndmask_b32_e64 v1, v1, v9, vcc
	v_sub_f32_e32 v20, v0, v255
	v_mul_f32_e32 v20, 0x3fb8aa3b, v20
	v_exp_f32_e32 v20, v20
	v_lshlrev_b32_e32 v50, 2, v1
	v_lshrrev_b64 v[52:53], v50, v[48:49]
	v_lshl_add_u32 v51, v1, 7, v135
	v_and_b32_e32 v52, 15, v52
	v_lshl_add_u32 v52, v52, 7, v206
	ds_read_u8 v53, v51
	ds_read_u8 v54, v52 offset:40960
	v_lshlrev_b64 v[50:51], v50, 1
	v_lshl_add_u64 v[48:49], v[50:51], 0, v[48:49]
	v_bfe_u32 v0, v48, 0, 4
	v_bfe_u32 v1, v48, 4, 4
	v_bfe_u32 v2, v48, 8, 4
	v_bfe_u32 v3, v48, 12, 4
	v_bfe_u32 v4, v48, 16, 4
	v_bfe_u32 v5, v48, 20, 4
	v_bfe_u32 v6, v48, 24, 4
	v_bfe_u32 v7, v48, 28, 4
	v_bfe_u32 v8, v49, 0, 4
	v_bfe_u32 v9, v49, 4, 4
	v_bfe_u32 v10, v49, 8, 4
	v_bfe_u32 v11, v49, 12, 4
	v_bfe_u32 v12, v49, 16, 4
	v_bfe_u32 v13, v49, 20, 4
	v_bfe_u32 v14, v49, 24, 4
	v_bfe_u32 v15, v49, 28, 4
	v_lshl_add_u32 v0, v0, 9, v134
	v_lshl_add_u32 v1, v1, 9, v134
	v_lshl_add_u32 v2, v2, 9, v134
	v_lshl_add_u32 v3, v3, 9, v134
	v_lshl_add_u32 v4, v4, 9, v134
	v_lshl_add_u32 v5, v5, 9, v134
	v_lshl_add_u32 v6, v6, 9, v134
	v_lshl_add_u32 v7, v7, 9, v134
	v_lshl_add_u32 v8, v8, 9, v134
	v_lshl_add_u32 v9, v9, 9, v134
	v_lshl_add_u32 v10, v10, 9, v134
	v_lshl_add_u32 v11, v11, 9, v134
	v_lshl_add_u32 v12, v12, 9, v134
	v_lshl_add_u32 v13, v13, 9, v134
	v_lshl_add_u32 v14, v14, 9, v134
	v_lshl_add_u32 v15, v15, 9, v134
	s_waitcnt lgkmcnt(0)
	v_lshl_add_u32 v53, v53, 7, v54
	global_store_dword v254, v53, s[38:39] offset:16
	ds_read_b32 v0, v0 offset:32768
	ds_read_b32 v1, v1 offset:32768
	ds_read_b32 v2, v2 offset:32768
	ds_read_b32 v3, v3 offset:32768
	ds_read_b32 v4, v4 offset:32768
	ds_read_b32 v5, v5 offset:32768
	ds_read_b32 v6, v6 offset:32768
	ds_read_b32 v7, v7 offset:32768
	ds_read_b32 v8, v8 offset:32768
	ds_read_b32 v9, v9 offset:32768
	ds_read_b32 v10, v10 offset:32768
	ds_read_b32 v11, v11 offset:32768
	ds_read_b32 v12, v12 offset:32768
	ds_read_b32 v13, v13 offset:32768
	ds_read_b32 v14, v14 offset:32768
	ds_read_b32 v15, v15 offset:32768
	s_waitcnt lgkmcnt(0)
	v_add_f32_e32 v0, v32, v0
	v_add_f32_e32 v1, v33, v1
	v_add_f32_e32 v2, v34, v2
	v_add_f32_e32 v3, v35, v3
	v_add_f32_e32 v4, v36, v4
	v_add_f32_e32 v5, v37, v5
	v_add_f32_e32 v6, v38, v6
	v_add_f32_e32 v7, v39, v7
	v_add_f32_e32 v8, v40, v8
	v_add_f32_e32 v9, v41, v9
	v_add_f32_e32 v10, v42, v10
	v_add_f32_e32 v11, v43, v11
	v_add_f32_e32 v12, v44, v12
	v_add_f32_e32 v13, v45, v13
	v_add_f32_e32 v14, v46, v14
	v_add_f32_e32 v15, v47, v15
	v_cmp_gt_f32_e32 vcc, v1, v0
	v_cmp_gt_f32_e64 s[8:9], v3, v2
	v_cmp_gt_f32_e64 s[98:99], v5, v4
	v_cmp_gt_f32_e64 s[100:101], v7, v6
	v_cndmask_b32_e64 v0, v0, v1, vcc
	v_cndmask_b32_e64 v1, 0, 1, vcc
	v_cndmask_b32_e64 v2, v2, v3, s[8:9]
	v_cndmask_b32_e64 v3, 2, 3, s[8:9]
	v_cndmask_b32_e64 v4, v4, v5, s[98:99]
	v_cndmask_b32_e64 v5, 4, 5, s[98:99]
	v_cndmask_b32_e64 v6, v6, v7, s[100:101]
	v_cndmask_b32_e64 v7, 6, 7, s[100:101]
	v_cmp_gt_f32_e32 vcc, v9, v8
	v_cmp_gt_f32_e64 s[8:9], v11, v10
	v_cmp_gt_f32_e64 s[98:99], v13, v12
	v_cmp_gt_f32_e64 s[100:101], v15, v14
	v_cndmask_b32_e64 v8, v8, v9, vcc
	v_cndmask_b32_e64 v9, 8, 9, vcc
	v_cndmask_b32_e64 v10, v10, v11, s[8:9]
	v_cndmask_b32_e64 v11, 10, 11, s[8:9]
	v_cndmask_b32_e64 v12, v12, v13, s[98:99]
	v_cndmask_b32_e64 v13, 12, 13, s[98:99]
	v_cndmask_b32_e64 v14, v14, v15, s[100:101]
	v_cndmask_b32_e64 v15, 14, 15, s[100:101]
	v_cmp_gt_f32_e32 vcc, v2, v0
	v_cmp_gt_f32_e64 s[8:9], v6, v4
	v_cmp_gt_f32_e64 s[98:99], v10, v8
	v_cmp_gt_f32_e64 s[100:101], v14, v12
	v_cndmask_b32_e64 v0, v0, v2, vcc
	v_cndmask_b32_e64 v1, v1, v3, vcc
	v_cndmask_b32_e64 v4, v4, v6, s[8:9]
	v_cndmask_b32_e64 v5, v5, v7, s[8:9]
	v_cndmask_b32_e64 v8, v8, v10, s[98:99]
	v_cndmask_b32_e64 v9, v9, v11, s[98:99]
	v_cndmask_b32_e64 v12, v12, v14, s[100:101]
	v_cndmask_b32_e64 v13, v13, v15, s[100:101]
	v_cmp_gt_f32_e32 vcc, v4, v0
	v_cmp_gt_f32_e64 s[8:9], v12, v8
	s_nop 0
	v_cndmask_b32_e64 v0, v0, v4, vcc
	v_cndmask_b32_e64 v1, v1, v5, vcc
	v_cndmask_b32_e64 v8, v8, v12, s[8:9]
	v_cndmask_b32_e64 v9, v9, v13, s[8:9]
	v_cmp_gt_f32_e32 vcc, v8, v0
	s_nop 1
	v_cndmask_b32_e64 v0, v0, v8, vcc
	v_cndmask_b32_e64 v1, v1, v9, vcc
	v_sub_f32_e32 v21, v0, v255
	v_mul_f32_e32 v21, 0x3fb8aa3b, v21
	v_exp_f32_e32 v21, v21
	v_lshlrev_b32_e32 v50, 2, v1
	v_lshrrev_b64 v[52:53], v50, v[48:49]
	v_lshl_add_u32 v51, v1, 7, v135
	v_and_b32_e32 v52, 15, v52
	v_lshl_add_u32 v52, v52, 7, v206
	ds_read_u8 v53, v51
	ds_read_u8 v54, v52 offset:40960
	v_lshlrev_b64 v[50:51], v50, 1
	v_lshl_add_u64 v[48:49], v[50:51], 0, v[48:49]
	v_bfe_u32 v0, v48, 0, 4
	v_bfe_u32 v1, v48, 4, 4
	v_bfe_u32 v2, v48, 8, 4
	v_bfe_u32 v3, v48, 12, 4
	v_bfe_u32 v4, v48, 16, 4
	v_bfe_u32 v5, v48, 20, 4
	v_bfe_u32 v6, v48, 24, 4
	v_bfe_u32 v7, v48, 28, 4
	v_bfe_u32 v8, v49, 0, 4
	v_bfe_u32 v9, v49, 4, 4
	v_bfe_u32 v10, v49, 8, 4
	v_bfe_u32 v11, v49, 12, 4
	v_bfe_u32 v12, v49, 16, 4
	v_bfe_u32 v13, v49, 20, 4
	v_bfe_u32 v14, v49, 24, 4
	v_bfe_u32 v15, v49, 28, 4
	v_lshl_add_u32 v0, v0, 9, v134
	v_lshl_add_u32 v1, v1, 9, v134
	v_lshl_add_u32 v2, v2, 9, v134
	v_lshl_add_u32 v3, v3, 9, v134
	v_lshl_add_u32 v4, v4, 9, v134
	v_lshl_add_u32 v5, v5, 9, v134
	v_lshl_add_u32 v6, v6, 9, v134
	v_lshl_add_u32 v7, v7, 9, v134
	v_lshl_add_u32 v8, v8, 9, v134
	v_lshl_add_u32 v9, v9, 9, v134
	v_lshl_add_u32 v10, v10, 9, v134
	v_lshl_add_u32 v11, v11, 9, v134
	v_lshl_add_u32 v12, v12, 9, v134
	v_lshl_add_u32 v13, v13, 9, v134
	v_lshl_add_u32 v14, v14, 9, v134
	v_lshl_add_u32 v15, v15, 9, v134
	s_waitcnt lgkmcnt(0)
	v_lshl_add_u32 v53, v53, 7, v54
	global_store_dword v254, v53, s[38:39] offset:20
	ds_read_b32 v0, v0 offset:32768
	ds_read_b32 v1, v1 offset:32768
	ds_read_b32 v2, v2 offset:32768
	ds_read_b32 v3, v3 offset:32768
	ds_read_b32 v4, v4 offset:32768
	ds_read_b32 v5, v5 offset:32768
	ds_read_b32 v6, v6 offset:32768
	ds_read_b32 v7, v7 offset:32768
	ds_read_b32 v8, v8 offset:32768
	ds_read_b32 v9, v9 offset:32768
	ds_read_b32 v10, v10 offset:32768
	ds_read_b32 v11, v11 offset:32768
	ds_read_b32 v12, v12 offset:32768
	ds_read_b32 v13, v13 offset:32768
	ds_read_b32 v14, v14 offset:32768
	ds_read_b32 v15, v15 offset:32768
	s_waitcnt lgkmcnt(0)
	v_add_f32_e32 v0, v32, v0
	v_add_f32_e32 v1, v33, v1
	v_add_f32_e32 v2, v34, v2
	v_add_f32_e32 v3, v35, v3
	v_add_f32_e32 v4, v36, v4
	v_add_f32_e32 v5, v37, v5
	v_add_f32_e32 v6, v38, v6
	v_add_f32_e32 v7, v39, v7
	v_add_f32_e32 v8, v40, v8
	v_add_f32_e32 v9, v41, v9
	v_add_f32_e32 v10, v42, v10
	v_add_f32_e32 v11, v43, v11
	v_add_f32_e32 v12, v44, v12
	v_add_f32_e32 v13, v45, v13
	v_add_f32_e32 v14, v46, v14
	v_add_f32_e32 v15, v47, v15
	v_cmp_gt_f32_e32 vcc, v1, v0
	v_cmp_gt_f32_e64 s[8:9], v3, v2
	v_cmp_gt_f32_e64 s[98:99], v5, v4
	v_cmp_gt_f32_e64 s[100:101], v7, v6
	v_cndmask_b32_e64 v0, v0, v1, vcc
	v_cndmask_b32_e64 v1, 0, 1, vcc
	v_cndmask_b32_e64 v2, v2, v3, s[8:9]
	v_cndmask_b32_e64 v3, 2, 3, s[8:9]
	v_cndmask_b32_e64 v4, v4, v5, s[98:99]
	v_cndmask_b32_e64 v5, 4, 5, s[98:99]
	v_cndmask_b32_e64 v6, v6, v7, s[100:101]
	v_cndmask_b32_e64 v7, 6, 7, s[100:101]
	v_cmp_gt_f32_e32 vcc, v9, v8
	v_cmp_gt_f32_e64 s[8:9], v11, v10
	v_cmp_gt_f32_e64 s[98:99], v13, v12
	v_cmp_gt_f32_e64 s[100:101], v15, v14
	v_cndmask_b32_e64 v8, v8, v9, vcc
	v_cndmask_b32_e64 v9, 8, 9, vcc
	v_cndmask_b32_e64 v10, v10, v11, s[8:9]
	v_cndmask_b32_e64 v11, 10, 11, s[8:9]
	v_cndmask_b32_e64 v12, v12, v13, s[98:99]
	v_cndmask_b32_e64 v13, 12, 13, s[98:99]
	v_cndmask_b32_e64 v14, v14, v15, s[100:101]
	v_cndmask_b32_e64 v15, 14, 15, s[100:101]
	v_cmp_gt_f32_e32 vcc, v2, v0
	v_cmp_gt_f32_e64 s[8:9], v6, v4
	v_cmp_gt_f32_e64 s[98:99], v10, v8
	v_cmp_gt_f32_e64 s[100:101], v14, v12
	v_cndmask_b32_e64 v0, v0, v2, vcc
	v_cndmask_b32_e64 v1, v1, v3, vcc
	v_cndmask_b32_e64 v4, v4, v6, s[8:9]
	v_cndmask_b32_e64 v5, v5, v7, s[8:9]
	v_cndmask_b32_e64 v8, v8, v10, s[98:99]
	v_cndmask_b32_e64 v9, v9, v11, s[98:99]
	v_cndmask_b32_e64 v12, v12, v14, s[100:101]
	v_cndmask_b32_e64 v13, v13, v15, s[100:101]
	v_cmp_gt_f32_e32 vcc, v4, v0
	v_cmp_gt_f32_e64 s[8:9], v12, v8
	s_nop 0
	v_cndmask_b32_e64 v0, v0, v4, vcc
	v_cndmask_b32_e64 v1, v1, v5, vcc
	v_cndmask_b32_e64 v8, v8, v12, s[8:9]
	v_cndmask_b32_e64 v9, v9, v13, s[8:9]
	v_cmp_gt_f32_e32 vcc, v8, v0
	s_nop 1
	v_cndmask_b32_e64 v0, v0, v8, vcc
	v_cndmask_b32_e64 v1, v1, v9, vcc
	v_sub_f32_e32 v22, v0, v255
	v_mul_f32_e32 v22, 0x3fb8aa3b, v22
	v_exp_f32_e32 v22, v22
	v_lshlrev_b32_e32 v50, 2, v1
	v_lshrrev_b64 v[52:53], v50, v[48:49]
	v_lshl_add_u32 v51, v1, 7, v135
	v_and_b32_e32 v52, 15, v52
	v_lshl_add_u32 v52, v52, 7, v206
	ds_read_u8 v53, v51
	ds_read_u8 v54, v52 offset:40960
	v_lshlrev_b64 v[50:51], v50, 1
	v_lshl_add_u64 v[48:49], v[50:51], 0, v[48:49]
	v_bfe_u32 v0, v48, 0, 4
	v_bfe_u32 v1, v48, 4, 4
	v_bfe_u32 v2, v48, 8, 4
	v_bfe_u32 v3, v48, 12, 4
	v_bfe_u32 v4, v48, 16, 4
	v_bfe_u32 v5, v48, 20, 4
	v_bfe_u32 v6, v48, 24, 4
	v_bfe_u32 v7, v48, 28, 4
	v_bfe_u32 v8, v49, 0, 4
	v_bfe_u32 v9, v49, 4, 4
	v_bfe_u32 v10, v49, 8, 4
	v_bfe_u32 v11, v49, 12, 4
	v_bfe_u32 v12, v49, 16, 4
	v_bfe_u32 v13, v49, 20, 4
	v_bfe_u32 v14, v49, 24, 4
	v_bfe_u32 v15, v49, 28, 4
	v_lshl_add_u32 v0, v0, 9, v134
	v_lshl_add_u32 v1, v1, 9, v134
	v_lshl_add_u32 v2, v2, 9, v134
	v_lshl_add_u32 v3, v3, 9, v134
	v_lshl_add_u32 v4, v4, 9, v134
	v_lshl_add_u32 v5, v5, 9, v134
	v_lshl_add_u32 v6, v6, 9, v134
	v_lshl_add_u32 v7, v7, 9, v134
	v_lshl_add_u32 v8, v8, 9, v134
	v_lshl_add_u32 v9, v9, 9, v134
	v_lshl_add_u32 v10, v10, 9, v134
	v_lshl_add_u32 v11, v11, 9, v134
	v_lshl_add_u32 v12, v12, 9, v134
	v_lshl_add_u32 v13, v13, 9, v134
	v_lshl_add_u32 v14, v14, 9, v134
	v_lshl_add_u32 v15, v15, 9, v134
	s_waitcnt lgkmcnt(0)
	v_lshl_add_u32 v53, v53, 7, v54
	global_store_dword v254, v53, s[38:39] offset:24
	ds_read_b32 v0, v0 offset:32768
	ds_read_b32 v1, v1 offset:32768
	ds_read_b32 v2, v2 offset:32768
	ds_read_b32 v3, v3 offset:32768
	ds_read_b32 v4, v4 offset:32768
	ds_read_b32 v5, v5 offset:32768
	ds_read_b32 v6, v6 offset:32768
	ds_read_b32 v7, v7 offset:32768
	ds_read_b32 v8, v8 offset:32768
	ds_read_b32 v9, v9 offset:32768
	ds_read_b32 v10, v10 offset:32768
	ds_read_b32 v11, v11 offset:32768
	ds_read_b32 v12, v12 offset:32768
	ds_read_b32 v13, v13 offset:32768
	ds_read_b32 v14, v14 offset:32768
	ds_read_b32 v15, v15 offset:32768
	s_waitcnt lgkmcnt(0)
	v_add_f32_e32 v0, v32, v0
	v_add_f32_e32 v1, v33, v1
	v_add_f32_e32 v2, v34, v2
	v_add_f32_e32 v3, v35, v3
	v_add_f32_e32 v4, v36, v4
	v_add_f32_e32 v5, v37, v5
	v_add_f32_e32 v6, v38, v6
	v_add_f32_e32 v7, v39, v7
	v_add_f32_e32 v8, v40, v8
	v_add_f32_e32 v9, v41, v9
	v_add_f32_e32 v10, v42, v10
	v_add_f32_e32 v11, v43, v11
	v_add_f32_e32 v12, v44, v12
	v_add_f32_e32 v13, v45, v13
	v_add_f32_e32 v14, v46, v14
	v_add_f32_e32 v15, v47, v15
	v_cmp_gt_f32_e32 vcc, v1, v0
	v_cmp_gt_f32_e64 s[8:9], v3, v2
	v_cmp_gt_f32_e64 s[98:99], v5, v4
	v_cmp_gt_f32_e64 s[100:101], v7, v6
	v_cndmask_b32_e64 v0, v0, v1, vcc
	v_cndmask_b32_e64 v1, 0, 1, vcc
	v_cndmask_b32_e64 v2, v2, v3, s[8:9]
	v_cndmask_b32_e64 v3, 2, 3, s[8:9]
	v_cndmask_b32_e64 v4, v4, v5, s[98:99]
	v_cndmask_b32_e64 v5, 4, 5, s[98:99]
	v_cndmask_b32_e64 v6, v6, v7, s[100:101]
	v_cndmask_b32_e64 v7, 6, 7, s[100:101]
	v_cmp_gt_f32_e32 vcc, v9, v8
	v_cmp_gt_f32_e64 s[8:9], v11, v10
	v_cmp_gt_f32_e64 s[98:99], v13, v12
	v_cmp_gt_f32_e64 s[100:101], v15, v14
	v_cndmask_b32_e64 v8, v8, v9, vcc
	v_cndmask_b32_e64 v9, 8, 9, vcc
	v_cndmask_b32_e64 v10, v10, v11, s[8:9]
	v_cndmask_b32_e64 v11, 10, 11, s[8:9]
	v_cndmask_b32_e64 v12, v12, v13, s[98:99]
	v_cndmask_b32_e64 v13, 12, 13, s[98:99]
	v_cndmask_b32_e64 v14, v14, v15, s[100:101]
	v_cndmask_b32_e64 v15, 14, 15, s[100:101]
	v_cmp_gt_f32_e32 vcc, v2, v0
	v_cmp_gt_f32_e64 s[8:9], v6, v4
	v_cmp_gt_f32_e64 s[98:99], v10, v8
	v_cmp_gt_f32_e64 s[100:101], v14, v12
	v_cndmask_b32_e64 v0, v0, v2, vcc
	v_cndmask_b32_e64 v1, v1, v3, vcc
	v_cndmask_b32_e64 v4, v4, v6, s[8:9]
	v_cndmask_b32_e64 v5, v5, v7, s[8:9]
	v_cndmask_b32_e64 v8, v8, v10, s[98:99]
	v_cndmask_b32_e64 v9, v9, v11, s[98:99]
	v_cndmask_b32_e64 v12, v12, v14, s[100:101]
	v_cndmask_b32_e64 v13, v13, v15, s[100:101]
	v_cmp_gt_f32_e32 vcc, v4, v0
	v_cmp_gt_f32_e64 s[8:9], v12, v8
	s_nop 0
	v_cndmask_b32_e64 v0, v0, v4, vcc
	v_cndmask_b32_e64 v1, v1, v5, vcc
	v_cndmask_b32_e64 v8, v8, v12, s[8:9]
	v_cndmask_b32_e64 v9, v9, v13, s[8:9]
	v_cmp_gt_f32_e32 vcc, v8, v0
	s_nop 1
	v_cndmask_b32_e64 v0, v0, v8, vcc
	v_cndmask_b32_e64 v1, v1, v9, vcc
	v_sub_f32_e32 v23, v0, v255
	v_mul_f32_e32 v23, 0x3fb8aa3b, v23
	v_exp_f32_e32 v23, v23
	v_lshlrev_b32_e32 v50, 2, v1
	v_lshrrev_b64 v[52:53], v50, v[48:49]
	v_lshl_add_u32 v51, v1, 7, v135
	v_and_b32_e32 v52, 15, v52
	v_lshl_add_u32 v52, v52, 7, v206
	ds_read_u8 v53, v51
	ds_read_u8 v54, v52 offset:40960
	v_lshlrev_b64 v[50:51], v50, 1
	v_lshl_add_u64 v[48:49], v[50:51], 0, v[48:49]
	v_bfe_u32 v0, v48, 0, 4
	v_bfe_u32 v1, v48, 4, 4
	v_bfe_u32 v2, v48, 8, 4
	v_bfe_u32 v3, v48, 12, 4
	v_bfe_u32 v4, v48, 16, 4
	v_bfe_u32 v5, v48, 20, 4
	v_bfe_u32 v6, v48, 24, 4
	v_bfe_u32 v7, v48, 28, 4
	v_bfe_u32 v8, v49, 0, 4
	v_bfe_u32 v9, v49, 4, 4
	v_bfe_u32 v10, v49, 8, 4
	v_bfe_u32 v11, v49, 12, 4
	v_bfe_u32 v12, v49, 16, 4
	v_bfe_u32 v13, v49, 20, 4
	v_bfe_u32 v14, v49, 24, 4
	v_bfe_u32 v15, v49, 28, 4
	v_lshl_add_u32 v0, v0, 9, v134
	v_lshl_add_u32 v1, v1, 9, v134
	v_lshl_add_u32 v2, v2, 9, v134
	v_lshl_add_u32 v3, v3, 9, v134
	v_lshl_add_u32 v4, v4, 9, v134
	v_lshl_add_u32 v5, v5, 9, v134
	v_lshl_add_u32 v6, v6, 9, v134
	v_lshl_add_u32 v7, v7, 9, v134
	v_lshl_add_u32 v8, v8, 9, v134
	v_lshl_add_u32 v9, v9, 9, v134
	v_lshl_add_u32 v10, v10, 9, v134
	v_lshl_add_u32 v11, v11, 9, v134
	v_lshl_add_u32 v12, v12, 9, v134
	v_lshl_add_u32 v13, v13, 9, v134
	v_lshl_add_u32 v14, v14, 9, v134
	v_lshl_add_u32 v15, v15, 9, v134
	s_waitcnt lgkmcnt(0)
	v_lshl_add_u32 v53, v53, 7, v54
	global_store_dword v254, v53, s[38:39] offset:28
	ds_read_b32 v0, v0 offset:32768
	ds_read_b32 v1, v1 offset:32768
	ds_read_b32 v2, v2 offset:32768
	ds_read_b32 v3, v3 offset:32768
	ds_read_b32 v4, v4 offset:32768
	ds_read_b32 v5, v5 offset:32768
	ds_read_b32 v6, v6 offset:32768
	ds_read_b32 v7, v7 offset:32768
	ds_read_b32 v8, v8 offset:32768
	ds_read_b32 v9, v9 offset:32768
	ds_read_b32 v10, v10 offset:32768
	ds_read_b32 v11, v11 offset:32768
	ds_read_b32 v12, v12 offset:32768
	ds_read_b32 v13, v13 offset:32768
	ds_read_b32 v14, v14 offset:32768
	ds_read_b32 v15, v15 offset:32768
	s_waitcnt lgkmcnt(0)
	v_add_f32_e32 v0, v32, v0
	v_add_f32_e32 v1, v33, v1
	v_add_f32_e32 v2, v34, v2
	v_add_f32_e32 v3, v35, v3
	v_add_f32_e32 v4, v36, v4
	v_add_f32_e32 v5, v37, v5
	v_add_f32_e32 v6, v38, v6
	v_add_f32_e32 v7, v39, v7
	v_add_f32_e32 v8, v40, v8
	v_add_f32_e32 v9, v41, v9
	v_add_f32_e32 v10, v42, v10
	v_add_f32_e32 v11, v43, v11
	v_add_f32_e32 v12, v44, v12
	v_add_f32_e32 v13, v45, v13
	v_add_f32_e32 v14, v46, v14
	v_add_f32_e32 v15, v47, v15
	v_cmp_gt_f32_e32 vcc, v1, v0
	v_cmp_gt_f32_e64 s[8:9], v3, v2
	v_cmp_gt_f32_e64 s[98:99], v5, v4
	v_cmp_gt_f32_e64 s[100:101], v7, v6
	v_cndmask_b32_e64 v0, v0, v1, vcc
	v_cndmask_b32_e64 v1, 0, 1, vcc
	v_cndmask_b32_e64 v2, v2, v3, s[8:9]
	v_cndmask_b32_e64 v3, 2, 3, s[8:9]
	v_cndmask_b32_e64 v4, v4, v5, s[98:99]
	v_cndmask_b32_e64 v5, 4, 5, s[98:99]
	v_cndmask_b32_e64 v6, v6, v7, s[100:101]
	v_cndmask_b32_e64 v7, 6, 7, s[100:101]
	v_cmp_gt_f32_e32 vcc, v9, v8
	v_cmp_gt_f32_e64 s[8:9], v11, v10
	v_cmp_gt_f32_e64 s[98:99], v13, v12
	v_cmp_gt_f32_e64 s[100:101], v15, v14
	v_cndmask_b32_e64 v8, v8, v9, vcc
	v_cndmask_b32_e64 v9, 8, 9, vcc
	v_cndmask_b32_e64 v10, v10, v11, s[8:9]
	v_cndmask_b32_e64 v11, 10, 11, s[8:9]
	v_cndmask_b32_e64 v12, v12, v13, s[98:99]
	v_cndmask_b32_e64 v13, 12, 13, s[98:99]
	v_cndmask_b32_e64 v14, v14, v15, s[100:101]
	v_cndmask_b32_e64 v15, 14, 15, s[100:101]
	v_cmp_gt_f32_e32 vcc, v2, v0
	v_cmp_gt_f32_e64 s[8:9], v6, v4
	v_cmp_gt_f32_e64 s[98:99], v10, v8
	v_cmp_gt_f32_e64 s[100:101], v14, v12
	v_cndmask_b32_e64 v0, v0, v2, vcc
	v_cndmask_b32_e64 v1, v1, v3, vcc
	v_cndmask_b32_e64 v4, v4, v6, s[8:9]
	v_cndmask_b32_e64 v5, v5, v7, s[8:9]
	v_cndmask_b32_e64 v8, v8, v10, s[98:99]
	v_cndmask_b32_e64 v9, v9, v11, s[98:99]
	v_cndmask_b32_e64 v12, v12, v14, s[100:101]
	v_cndmask_b32_e64 v13, v13, v15, s[100:101]
	v_cmp_gt_f32_e32 vcc, v4, v0
	v_cmp_gt_f32_e64 s[8:9], v12, v8
	s_nop 0
	v_cndmask_b32_e64 v0, v0, v4, vcc
	v_cndmask_b32_e64 v1, v1, v5, vcc
	v_cndmask_b32_e64 v8, v8, v12, s[8:9]
	v_cndmask_b32_e64 v9, v9, v13, s[8:9]
	v_cmp_gt_f32_e32 vcc, v8, v0
	s_nop 1
	v_cndmask_b32_e64 v0, v0, v8, vcc
	v_cndmask_b32_e64 v1, v1, v9, vcc
	v_sub_f32_e32 v24, v0, v255
	v_mul_f32_e32 v24, 0x3fb8aa3b, v24
	v_exp_f32_e32 v24, v24
	v_lshlrev_b32_e32 v50, 2, v1
	v_lshrrev_b64 v[52:53], v50, v[48:49]
	v_lshl_add_u32 v51, v1, 7, v135
	v_and_b32_e32 v52, 15, v52
	v_lshl_add_u32 v52, v52, 7, v206
	ds_read_u8 v53, v51
	ds_read_u8 v54, v52 offset:40960
	v_lshlrev_b64 v[50:51], v50, 1
	v_lshl_add_u64 v[48:49], v[50:51], 0, v[48:49]
	v_bfe_u32 v0, v48, 0, 4
	v_bfe_u32 v1, v48, 4, 4
	v_bfe_u32 v2, v48, 8, 4
	v_bfe_u32 v3, v48, 12, 4
	v_bfe_u32 v4, v48, 16, 4
	v_bfe_u32 v5, v48, 20, 4
	v_bfe_u32 v6, v48, 24, 4
	v_bfe_u32 v7, v48, 28, 4
	v_bfe_u32 v8, v49, 0, 4
	v_bfe_u32 v9, v49, 4, 4
	v_bfe_u32 v10, v49, 8, 4
	v_bfe_u32 v11, v49, 12, 4
	v_bfe_u32 v12, v49, 16, 4
	v_bfe_u32 v13, v49, 20, 4
	v_bfe_u32 v14, v49, 24, 4
	v_bfe_u32 v15, v49, 28, 4
	v_lshl_add_u32 v0, v0, 9, v134
	v_lshl_add_u32 v1, v1, 9, v134
	v_lshl_add_u32 v2, v2, 9, v134
	v_lshl_add_u32 v3, v3, 9, v134
	v_lshl_add_u32 v4, v4, 9, v134
	v_lshl_add_u32 v5, v5, 9, v134
	v_lshl_add_u32 v6, v6, 9, v134
	v_lshl_add_u32 v7, v7, 9, v134
	v_lshl_add_u32 v8, v8, 9, v134
	v_lshl_add_u32 v9, v9, 9, v134
	v_lshl_add_u32 v10, v10, 9, v134
	v_lshl_add_u32 v11, v11, 9, v134
	v_lshl_add_u32 v12, v12, 9, v134
	v_lshl_add_u32 v13, v13, 9, v134
	v_lshl_add_u32 v14, v14, 9, v134
	v_lshl_add_u32 v15, v15, 9, v134
	s_waitcnt lgkmcnt(0)
	v_lshl_add_u32 v53, v53, 7, v54
	global_store_dword v254, v53, s[38:39] offset:32
	ds_read_b32 v0, v0 offset:32768
	ds_read_b32 v1, v1 offset:32768
	ds_read_b32 v2, v2 offset:32768
	ds_read_b32 v3, v3 offset:32768
	ds_read_b32 v4, v4 offset:32768
	ds_read_b32 v5, v5 offset:32768
	ds_read_b32 v6, v6 offset:32768
	ds_read_b32 v7, v7 offset:32768
	ds_read_b32 v8, v8 offset:32768
	ds_read_b32 v9, v9 offset:32768
	ds_read_b32 v10, v10 offset:32768
	ds_read_b32 v11, v11 offset:32768
	ds_read_b32 v12, v12 offset:32768
	ds_read_b32 v13, v13 offset:32768
	ds_read_b32 v14, v14 offset:32768
	ds_read_b32 v15, v15 offset:32768
	s_waitcnt lgkmcnt(0)
	v_add_f32_e32 v0, v32, v0
	v_add_f32_e32 v1, v33, v1
	v_add_f32_e32 v2, v34, v2
	v_add_f32_e32 v3, v35, v3
	v_add_f32_e32 v4, v36, v4
	v_add_f32_e32 v5, v37, v5
	v_add_f32_e32 v6, v38, v6
	v_add_f32_e32 v7, v39, v7
	v_add_f32_e32 v8, v40, v8
	v_add_f32_e32 v9, v41, v9
	v_add_f32_e32 v10, v42, v10
	v_add_f32_e32 v11, v43, v11
	v_add_f32_e32 v12, v44, v12
	v_add_f32_e32 v13, v45, v13
	v_add_f32_e32 v14, v46, v14
	v_add_f32_e32 v15, v47, v15
	v_cmp_gt_f32_e32 vcc, v1, v0
	v_cmp_gt_f32_e64 s[8:9], v3, v2
	v_cmp_gt_f32_e64 s[98:99], v5, v4
	v_cmp_gt_f32_e64 s[100:101], v7, v6
	v_cndmask_b32_e64 v0, v0, v1, vcc
	v_cndmask_b32_e64 v1, 0, 1, vcc
	v_cndmask_b32_e64 v2, v2, v3, s[8:9]
	v_cndmask_b32_e64 v3, 2, 3, s[8:9]
	v_cndmask_b32_e64 v4, v4, v5, s[98:99]
	v_cndmask_b32_e64 v5, 4, 5, s[98:99]
	v_cndmask_b32_e64 v6, v6, v7, s[100:101]
	v_cndmask_b32_e64 v7, 6, 7, s[100:101]
	v_cmp_gt_f32_e32 vcc, v9, v8
	v_cmp_gt_f32_e64 s[8:9], v11, v10
	v_cmp_gt_f32_e64 s[98:99], v13, v12
	v_cmp_gt_f32_e64 s[100:101], v15, v14
	v_cndmask_b32_e64 v8, v8, v9, vcc
	v_cndmask_b32_e64 v9, 8, 9, vcc
	v_cndmask_b32_e64 v10, v10, v11, s[8:9]
	v_cndmask_b32_e64 v11, 10, 11, s[8:9]
	v_cndmask_b32_e64 v12, v12, v13, s[98:99]
	v_cndmask_b32_e64 v13, 12, 13, s[98:99]
	v_cndmask_b32_e64 v14, v14, v15, s[100:101]
	v_cndmask_b32_e64 v15, 14, 15, s[100:101]
	v_cmp_gt_f32_e32 vcc, v2, v0
	v_cmp_gt_f32_e64 s[8:9], v6, v4
	v_cmp_gt_f32_e64 s[98:99], v10, v8
	v_cmp_gt_f32_e64 s[100:101], v14, v12
	v_cndmask_b32_e64 v0, v0, v2, vcc
	v_cndmask_b32_e64 v1, v1, v3, vcc
	v_cndmask_b32_e64 v4, v4, v6, s[8:9]
	v_cndmask_b32_e64 v5, v5, v7, s[8:9]
	v_cndmask_b32_e64 v8, v8, v10, s[98:99]
	v_cndmask_b32_e64 v9, v9, v11, s[98:99]
	v_cndmask_b32_e64 v12, v12, v14, s[100:101]
	v_cndmask_b32_e64 v13, v13, v15, s[100:101]
	v_cmp_gt_f32_e32 vcc, v4, v0
	v_cmp_gt_f32_e64 s[8:9], v12, v8
	s_nop 0
	v_cndmask_b32_e64 v0, v0, v4, vcc
	v_cndmask_b32_e64 v1, v1, v5, vcc
	v_cndmask_b32_e64 v8, v8, v12, s[8:9]
	v_cndmask_b32_e64 v9, v9, v13, s[8:9]
	v_cmp_gt_f32_e32 vcc, v8, v0
	s_nop 1
	v_cndmask_b32_e64 v0, v0, v8, vcc
	v_cndmask_b32_e64 v1, v1, v9, vcc
	v_sub_f32_e32 v25, v0, v255
	v_mul_f32_e32 v25, 0x3fb8aa3b, v25
	v_exp_f32_e32 v25, v25
	v_lshlrev_b32_e32 v50, 2, v1
	v_lshrrev_b64 v[52:53], v50, v[48:49]
	v_lshl_add_u32 v51, v1, 7, v135
	v_and_b32_e32 v52, 15, v52
	v_lshl_add_u32 v52, v52, 7, v206
	ds_read_u8 v53, v51
	ds_read_u8 v54, v52 offset:40960
	v_lshlrev_b64 v[50:51], v50, 1
	v_lshl_add_u64 v[48:49], v[50:51], 0, v[48:49]
	v_bfe_u32 v0, v48, 0, 4
	v_bfe_u32 v1, v48, 4, 4
	v_bfe_u32 v2, v48, 8, 4
	v_bfe_u32 v3, v48, 12, 4
	v_bfe_u32 v4, v48, 16, 4
	v_bfe_u32 v5, v48, 20, 4
	v_bfe_u32 v6, v48, 24, 4
	v_bfe_u32 v7, v48, 28, 4
	v_bfe_u32 v8, v49, 0, 4
	v_bfe_u32 v9, v49, 4, 4
	v_bfe_u32 v10, v49, 8, 4
	v_bfe_u32 v11, v49, 12, 4
	v_bfe_u32 v12, v49, 16, 4
	v_bfe_u32 v13, v49, 20, 4
	v_bfe_u32 v14, v49, 24, 4
	v_bfe_u32 v15, v49, 28, 4
	v_lshl_add_u32 v0, v0, 9, v134
	v_lshl_add_u32 v1, v1, 9, v134
	v_lshl_add_u32 v2, v2, 9, v134
	v_lshl_add_u32 v3, v3, 9, v134
	v_lshl_add_u32 v4, v4, 9, v134
	v_lshl_add_u32 v5, v5, 9, v134
	v_lshl_add_u32 v6, v6, 9, v134
	v_lshl_add_u32 v7, v7, 9, v134
	v_lshl_add_u32 v8, v8, 9, v134
	v_lshl_add_u32 v9, v9, 9, v134
	v_lshl_add_u32 v10, v10, 9, v134
	v_lshl_add_u32 v11, v11, 9, v134
	v_lshl_add_u32 v12, v12, 9, v134
	v_lshl_add_u32 v13, v13, 9, v134
	v_lshl_add_u32 v14, v14, 9, v134
	v_lshl_add_u32 v15, v15, 9, v134
	s_waitcnt lgkmcnt(0)
	v_lshl_add_u32 v53, v53, 7, v54
	global_store_dword v254, v53, s[38:39] offset:36
	ds_read_b32 v0, v0 offset:32768
	ds_read_b32 v1, v1 offset:32768
	ds_read_b32 v2, v2 offset:32768
	ds_read_b32 v3, v3 offset:32768
	ds_read_b32 v4, v4 offset:32768
	ds_read_b32 v5, v5 offset:32768
	ds_read_b32 v6, v6 offset:32768
	ds_read_b32 v7, v7 offset:32768
	ds_read_b32 v8, v8 offset:32768
	ds_read_b32 v9, v9 offset:32768
	ds_read_b32 v10, v10 offset:32768
	ds_read_b32 v11, v11 offset:32768
	ds_read_b32 v12, v12 offset:32768
	ds_read_b32 v13, v13 offset:32768
	ds_read_b32 v14, v14 offset:32768
	ds_read_b32 v15, v15 offset:32768
	s_waitcnt lgkmcnt(0)
	v_add_f32_e32 v0, v32, v0
	v_add_f32_e32 v1, v33, v1
	v_add_f32_e32 v2, v34, v2
	v_add_f32_e32 v3, v35, v3
	v_add_f32_e32 v4, v36, v4
	v_add_f32_e32 v5, v37, v5
	v_add_f32_e32 v6, v38, v6
	v_add_f32_e32 v7, v39, v7
	v_add_f32_e32 v8, v40, v8
	v_add_f32_e32 v9, v41, v9
	v_add_f32_e32 v10, v42, v10
	v_add_f32_e32 v11, v43, v11
	v_add_f32_e32 v12, v44, v12
	v_add_f32_e32 v13, v45, v13
	v_add_f32_e32 v14, v46, v14
	v_add_f32_e32 v15, v47, v15
	v_cmp_gt_f32_e32 vcc, v1, v0
	v_cmp_gt_f32_e64 s[8:9], v3, v2
	v_cmp_gt_f32_e64 s[98:99], v5, v4
	v_cmp_gt_f32_e64 s[100:101], v7, v6
	v_cndmask_b32_e64 v0, v0, v1, vcc
	v_cndmask_b32_e64 v1, 0, 1, vcc
	v_cndmask_b32_e64 v2, v2, v3, s[8:9]
	v_cndmask_b32_e64 v3, 2, 3, s[8:9]
	v_cndmask_b32_e64 v4, v4, v5, s[98:99]
	v_cndmask_b32_e64 v5, 4, 5, s[98:99]
	v_cndmask_b32_e64 v6, v6, v7, s[100:101]
	v_cndmask_b32_e64 v7, 6, 7, s[100:101]
	v_cmp_gt_f32_e32 vcc, v9, v8
	v_cmp_gt_f32_e64 s[8:9], v11, v10
	v_cmp_gt_f32_e64 s[98:99], v13, v12
	v_cmp_gt_f32_e64 s[100:101], v15, v14
	v_cndmask_b32_e64 v8, v8, v9, vcc
	v_cndmask_b32_e64 v9, 8, 9, vcc
	v_cndmask_b32_e64 v10, v10, v11, s[8:9]
	v_cndmask_b32_e64 v11, 10, 11, s[8:9]
	v_cndmask_b32_e64 v12, v12, v13, s[98:99]
	v_cndmask_b32_e64 v13, 12, 13, s[98:99]
	v_cndmask_b32_e64 v14, v14, v15, s[100:101]
	v_cndmask_b32_e64 v15, 14, 15, s[100:101]
	v_cmp_gt_f32_e32 vcc, v2, v0
	v_cmp_gt_f32_e64 s[8:9], v6, v4
	v_cmp_gt_f32_e64 s[98:99], v10, v8
	v_cmp_gt_f32_e64 s[100:101], v14, v12
	v_cndmask_b32_e64 v0, v0, v2, vcc
	v_cndmask_b32_e64 v1, v1, v3, vcc
	v_cndmask_b32_e64 v4, v4, v6, s[8:9]
	v_cndmask_b32_e64 v5, v5, v7, s[8:9]
	v_cndmask_b32_e64 v8, v8, v10, s[98:99]
	v_cndmask_b32_e64 v9, v9, v11, s[98:99]
	v_cndmask_b32_e64 v12, v12, v14, s[100:101]
	v_cndmask_b32_e64 v13, v13, v15, s[100:101]
	v_cmp_gt_f32_e32 vcc, v4, v0
	v_cmp_gt_f32_e64 s[8:9], v12, v8
	s_nop 0
	v_cndmask_b32_e64 v0, v0, v4, vcc
	v_cndmask_b32_e64 v1, v1, v5, vcc
	v_cndmask_b32_e64 v8, v8, v12, s[8:9]
	v_cndmask_b32_e64 v9, v9, v13, s[8:9]
	v_cmp_gt_f32_e32 vcc, v8, v0
	s_nop 1
	v_cndmask_b32_e64 v0, v0, v8, vcc
	v_cndmask_b32_e64 v1, v1, v9, vcc
	v_sub_f32_e32 v26, v0, v255
	v_mul_f32_e32 v26, 0x3fb8aa3b, v26
	v_exp_f32_e32 v26, v26
	v_lshlrev_b32_e32 v50, 2, v1
	v_lshrrev_b64 v[52:53], v50, v[48:49]
	v_lshl_add_u32 v51, v1, 7, v135
	v_and_b32_e32 v52, 15, v52
	v_lshl_add_u32 v52, v52, 7, v206
	ds_read_u8 v53, v51
	ds_read_u8 v54, v52 offset:40960
	v_lshlrev_b64 v[50:51], v50, 1
	v_lshl_add_u64 v[48:49], v[50:51], 0, v[48:49]
	v_bfe_u32 v0, v48, 0, 4
	v_bfe_u32 v1, v48, 4, 4
	v_bfe_u32 v2, v48, 8, 4
	v_bfe_u32 v3, v48, 12, 4
	v_bfe_u32 v4, v48, 16, 4
	v_bfe_u32 v5, v48, 20, 4
	v_bfe_u32 v6, v48, 24, 4
	v_bfe_u32 v7, v48, 28, 4
	v_bfe_u32 v8, v49, 0, 4
	v_bfe_u32 v9, v49, 4, 4
	v_bfe_u32 v10, v49, 8, 4
	v_bfe_u32 v11, v49, 12, 4
	v_bfe_u32 v12, v49, 16, 4
	v_bfe_u32 v13, v49, 20, 4
	v_bfe_u32 v14, v49, 24, 4
	v_bfe_u32 v15, v49, 28, 4
	v_lshl_add_u32 v0, v0, 9, v134
	v_lshl_add_u32 v1, v1, 9, v134
	v_lshl_add_u32 v2, v2, 9, v134
	v_lshl_add_u32 v3, v3, 9, v134
	v_lshl_add_u32 v4, v4, 9, v134
	v_lshl_add_u32 v5, v5, 9, v134
	v_lshl_add_u32 v6, v6, 9, v134
	v_lshl_add_u32 v7, v7, 9, v134
	v_lshl_add_u32 v8, v8, 9, v134
	v_lshl_add_u32 v9, v9, 9, v134
	v_lshl_add_u32 v10, v10, 9, v134
	v_lshl_add_u32 v11, v11, 9, v134
	v_lshl_add_u32 v12, v12, 9, v134
	v_lshl_add_u32 v13, v13, 9, v134
	v_lshl_add_u32 v14, v14, 9, v134
	v_lshl_add_u32 v15, v15, 9, v134
	s_waitcnt lgkmcnt(0)
	v_lshl_add_u32 v53, v53, 7, v54
	global_store_dword v254, v53, s[38:39] offset:40
	ds_read_b32 v0, v0 offset:32768
	ds_read_b32 v1, v1 offset:32768
	ds_read_b32 v2, v2 offset:32768
	ds_read_b32 v3, v3 offset:32768
	ds_read_b32 v4, v4 offset:32768
	ds_read_b32 v5, v5 offset:32768
	ds_read_b32 v6, v6 offset:32768
	ds_read_b32 v7, v7 offset:32768
	ds_read_b32 v8, v8 offset:32768
	ds_read_b32 v9, v9 offset:32768
	ds_read_b32 v10, v10 offset:32768
	ds_read_b32 v11, v11 offset:32768
	ds_read_b32 v12, v12 offset:32768
	ds_read_b32 v13, v13 offset:32768
	ds_read_b32 v14, v14 offset:32768
	ds_read_b32 v15, v15 offset:32768
	s_waitcnt lgkmcnt(0)
	v_add_f32_e32 v0, v32, v0
	v_add_f32_e32 v1, v33, v1
	v_add_f32_e32 v2, v34, v2
	v_add_f32_e32 v3, v35, v3
	v_add_f32_e32 v4, v36, v4
	v_add_f32_e32 v5, v37, v5
	v_add_f32_e32 v6, v38, v6
	v_add_f32_e32 v7, v39, v7
	v_add_f32_e32 v8, v40, v8
	v_add_f32_e32 v9, v41, v9
	v_add_f32_e32 v10, v42, v10
	v_add_f32_e32 v11, v43, v11
	v_add_f32_e32 v12, v44, v12
	v_add_f32_e32 v13, v45, v13
	v_add_f32_e32 v14, v46, v14
	v_add_f32_e32 v15, v47, v15
	v_cmp_gt_f32_e32 vcc, v1, v0
	v_cmp_gt_f32_e64 s[8:9], v3, v2
	v_cmp_gt_f32_e64 s[98:99], v5, v4
	v_cmp_gt_f32_e64 s[100:101], v7, v6
	v_cndmask_b32_e64 v0, v0, v1, vcc
	v_cndmask_b32_e64 v1, 0, 1, vcc
	v_cndmask_b32_e64 v2, v2, v3, s[8:9]
	v_cndmask_b32_e64 v3, 2, 3, s[8:9]
	v_cndmask_b32_e64 v4, v4, v5, s[98:99]
	v_cndmask_b32_e64 v5, 4, 5, s[98:99]
	v_cndmask_b32_e64 v6, v6, v7, s[100:101]
	v_cndmask_b32_e64 v7, 6, 7, s[100:101]
	v_cmp_gt_f32_e32 vcc, v9, v8
	v_cmp_gt_f32_e64 s[8:9], v11, v10
	v_cmp_gt_f32_e64 s[98:99], v13, v12
	v_cmp_gt_f32_e64 s[100:101], v15, v14
	v_cndmask_b32_e64 v8, v8, v9, vcc
	v_cndmask_b32_e64 v9, 8, 9, vcc
	v_cndmask_b32_e64 v10, v10, v11, s[8:9]
	v_cndmask_b32_e64 v11, 10, 11, s[8:9]
	v_cndmask_b32_e64 v12, v12, v13, s[98:99]
	v_cndmask_b32_e64 v13, 12, 13, s[98:99]
	v_cndmask_b32_e64 v14, v14, v15, s[100:101]
	v_cndmask_b32_e64 v15, 14, 15, s[100:101]
	v_cmp_gt_f32_e32 vcc, v2, v0
	v_cmp_gt_f32_e64 s[8:9], v6, v4
	v_cmp_gt_f32_e64 s[98:99], v10, v8
	v_cmp_gt_f32_e64 s[100:101], v14, v12
	v_cndmask_b32_e64 v0, v0, v2, vcc
	v_cndmask_b32_e64 v1, v1, v3, vcc
	v_cndmask_b32_e64 v4, v4, v6, s[8:9]
	v_cndmask_b32_e64 v5, v5, v7, s[8:9]
	v_cndmask_b32_e64 v8, v8, v10, s[98:99]
	v_cndmask_b32_e64 v9, v9, v11, s[98:99]
	v_cndmask_b32_e64 v12, v12, v14, s[100:101]
	v_cndmask_b32_e64 v13, v13, v15, s[100:101]
	v_cmp_gt_f32_e32 vcc, v4, v0
	v_cmp_gt_f32_e64 s[8:9], v12, v8
	s_nop 0
	v_cndmask_b32_e64 v0, v0, v4, vcc
	v_cndmask_b32_e64 v1, v1, v5, vcc
	v_cndmask_b32_e64 v8, v8, v12, s[8:9]
	v_cndmask_b32_e64 v9, v9, v13, s[8:9]
	v_cmp_gt_f32_e32 vcc, v8, v0
	s_nop 1
	v_cndmask_b32_e64 v0, v0, v8, vcc
	v_cndmask_b32_e64 v1, v1, v9, vcc
	v_sub_f32_e32 v27, v0, v255
	v_mul_f32_e32 v27, 0x3fb8aa3b, v27
	v_exp_f32_e32 v27, v27
	v_lshlrev_b32_e32 v50, 2, v1
	v_lshrrev_b64 v[52:53], v50, v[48:49]
	v_lshl_add_u32 v51, v1, 7, v135
	v_and_b32_e32 v52, 15, v52
	v_lshl_add_u32 v52, v52, 7, v206
	ds_read_u8 v53, v51
	ds_read_u8 v54, v52 offset:40960
	v_lshlrev_b64 v[50:51], v50, 1
	v_lshl_add_u64 v[48:49], v[50:51], 0, v[48:49]
	v_bfe_u32 v0, v48, 0, 4
	v_bfe_u32 v1, v48, 4, 4
	v_bfe_u32 v2, v48, 8, 4
	v_bfe_u32 v3, v48, 12, 4
	v_bfe_u32 v4, v48, 16, 4
	v_bfe_u32 v5, v48, 20, 4
	v_bfe_u32 v6, v48, 24, 4
	v_bfe_u32 v7, v48, 28, 4
	v_bfe_u32 v8, v49, 0, 4
	v_bfe_u32 v9, v49, 4, 4
	v_bfe_u32 v10, v49, 8, 4
	v_bfe_u32 v11, v49, 12, 4
	v_bfe_u32 v12, v49, 16, 4
	v_bfe_u32 v13, v49, 20, 4
	v_bfe_u32 v14, v49, 24, 4
	v_bfe_u32 v15, v49, 28, 4
	v_lshl_add_u32 v0, v0, 9, v134
	v_lshl_add_u32 v1, v1, 9, v134
	v_lshl_add_u32 v2, v2, 9, v134
	v_lshl_add_u32 v3, v3, 9, v134
	v_lshl_add_u32 v4, v4, 9, v134
	v_lshl_add_u32 v5, v5, 9, v134
	v_lshl_add_u32 v6, v6, 9, v134
	v_lshl_add_u32 v7, v7, 9, v134
	v_lshl_add_u32 v8, v8, 9, v134
	v_lshl_add_u32 v9, v9, 9, v134
	v_lshl_add_u32 v10, v10, 9, v134
	v_lshl_add_u32 v11, v11, 9, v134
	v_lshl_add_u32 v12, v12, 9, v134
	v_lshl_add_u32 v13, v13, 9, v134
	v_lshl_add_u32 v14, v14, 9, v134
	v_lshl_add_u32 v15, v15, 9, v134
	s_waitcnt lgkmcnt(0)
	v_lshl_add_u32 v53, v53, 7, v54
	global_store_dword v254, v53, s[38:39] offset:44
	ds_read_b32 v0, v0 offset:32768
	ds_read_b32 v1, v1 offset:32768
	ds_read_b32 v2, v2 offset:32768
	ds_read_b32 v3, v3 offset:32768
	ds_read_b32 v4, v4 offset:32768
	ds_read_b32 v5, v5 offset:32768
	ds_read_b32 v6, v6 offset:32768
	ds_read_b32 v7, v7 offset:32768
	ds_read_b32 v8, v8 offset:32768
	ds_read_b32 v9, v9 offset:32768
	ds_read_b32 v10, v10 offset:32768
	ds_read_b32 v11, v11 offset:32768
	ds_read_b32 v12, v12 offset:32768
	ds_read_b32 v13, v13 offset:32768
	ds_read_b32 v14, v14 offset:32768
	ds_read_b32 v15, v15 offset:32768
	s_waitcnt lgkmcnt(0)
	v_add_f32_e32 v0, v32, v0
	v_add_f32_e32 v1, v33, v1
	v_add_f32_e32 v2, v34, v2
	v_add_f32_e32 v3, v35, v3
	v_add_f32_e32 v4, v36, v4
	v_add_f32_e32 v5, v37, v5
	v_add_f32_e32 v6, v38, v6
	v_add_f32_e32 v7, v39, v7
	v_add_f32_e32 v8, v40, v8
	v_add_f32_e32 v9, v41, v9
	v_add_f32_e32 v10, v42, v10
	v_add_f32_e32 v11, v43, v11
	v_add_f32_e32 v12, v44, v12
	v_add_f32_e32 v13, v45, v13
	v_add_f32_e32 v14, v46, v14
	v_add_f32_e32 v15, v47, v15
	v_cmp_gt_f32_e32 vcc, v1, v0
	v_cmp_gt_f32_e64 s[8:9], v3, v2
	v_cmp_gt_f32_e64 s[98:99], v5, v4
	v_cmp_gt_f32_e64 s[100:101], v7, v6
	v_cndmask_b32_e64 v0, v0, v1, vcc
	v_cndmask_b32_e64 v1, 0, 1, vcc
	v_cndmask_b32_e64 v2, v2, v3, s[8:9]
	v_cndmask_b32_e64 v3, 2, 3, s[8:9]
	v_cndmask_b32_e64 v4, v4, v5, s[98:99]
	v_cndmask_b32_e64 v5, 4, 5, s[98:99]
	v_cndmask_b32_e64 v6, v6, v7, s[100:101]
	v_cndmask_b32_e64 v7, 6, 7, s[100:101]
	v_cmp_gt_f32_e32 vcc, v9, v8
	v_cmp_gt_f32_e64 s[8:9], v11, v10
	v_cmp_gt_f32_e64 s[98:99], v13, v12
	v_cmp_gt_f32_e64 s[100:101], v15, v14
	v_cndmask_b32_e64 v8, v8, v9, vcc
	v_cndmask_b32_e64 v9, 8, 9, vcc
	v_cndmask_b32_e64 v10, v10, v11, s[8:9]
	v_cndmask_b32_e64 v11, 10, 11, s[8:9]
	v_cndmask_b32_e64 v12, v12, v13, s[98:99]
	v_cndmask_b32_e64 v13, 12, 13, s[98:99]
	v_cndmask_b32_e64 v14, v14, v15, s[100:101]
	v_cndmask_b32_e64 v15, 14, 15, s[100:101]
	v_cmp_gt_f32_e32 vcc, v2, v0
	v_cmp_gt_f32_e64 s[8:9], v6, v4
	v_cmp_gt_f32_e64 s[98:99], v10, v8
	v_cmp_gt_f32_e64 s[100:101], v14, v12
	v_cndmask_b32_e64 v0, v0, v2, vcc
	v_cndmask_b32_e64 v1, v1, v3, vcc
	v_cndmask_b32_e64 v4, v4, v6, s[8:9]
	v_cndmask_b32_e64 v5, v5, v7, s[8:9]
	v_cndmask_b32_e64 v8, v8, v10, s[98:99]
	v_cndmask_b32_e64 v9, v9, v11, s[98:99]
	v_cndmask_b32_e64 v12, v12, v14, s[100:101]
	v_cndmask_b32_e64 v13, v13, v15, s[100:101]
	v_cmp_gt_f32_e32 vcc, v4, v0
	v_cmp_gt_f32_e64 s[8:9], v12, v8
	s_nop 0
	v_cndmask_b32_e64 v0, v0, v4, vcc
	v_cndmask_b32_e64 v1, v1, v5, vcc
	v_cndmask_b32_e64 v8, v8, v12, s[8:9]
	v_cndmask_b32_e64 v9, v9, v13, s[8:9]
	v_cmp_gt_f32_e32 vcc, v8, v0
	s_nop 1
	v_cndmask_b32_e64 v0, v0, v8, vcc
	v_cndmask_b32_e64 v1, v1, v9, vcc
	v_sub_f32_e32 v28, v0, v255
	v_mul_f32_e32 v28, 0x3fb8aa3b, v28
	v_exp_f32_e32 v28, v28
	v_lshlrev_b32_e32 v50, 2, v1
	v_lshrrev_b64 v[52:53], v50, v[48:49]
	v_lshl_add_u32 v51, v1, 7, v135
	v_and_b32_e32 v52, 15, v52
	v_lshl_add_u32 v52, v52, 7, v206
	ds_read_u8 v53, v51
	ds_read_u8 v54, v52 offset:40960
	v_lshlrev_b64 v[50:51], v50, 1
	v_lshl_add_u64 v[48:49], v[50:51], 0, v[48:49]
	v_bfe_u32 v0, v48, 0, 4
	v_bfe_u32 v1, v48, 4, 4
	v_bfe_u32 v2, v48, 8, 4
	v_bfe_u32 v3, v48, 12, 4
	v_bfe_u32 v4, v48, 16, 4
	v_bfe_u32 v5, v48, 20, 4
	v_bfe_u32 v6, v48, 24, 4
	v_bfe_u32 v7, v48, 28, 4
	v_bfe_u32 v8, v49, 0, 4
	v_bfe_u32 v9, v49, 4, 4
	v_bfe_u32 v10, v49, 8, 4
	v_bfe_u32 v11, v49, 12, 4
	v_bfe_u32 v12, v49, 16, 4
	v_bfe_u32 v13, v49, 20, 4
	v_bfe_u32 v14, v49, 24, 4
	v_bfe_u32 v15, v49, 28, 4
	v_lshl_add_u32 v0, v0, 9, v134
	v_lshl_add_u32 v1, v1, 9, v134
	v_lshl_add_u32 v2, v2, 9, v134
	v_lshl_add_u32 v3, v3, 9, v134
	v_lshl_add_u32 v4, v4, 9, v134
	v_lshl_add_u32 v5, v5, 9, v134
	v_lshl_add_u32 v6, v6, 9, v134
	v_lshl_add_u32 v7, v7, 9, v134
	v_lshl_add_u32 v8, v8, 9, v134
	v_lshl_add_u32 v9, v9, 9, v134
	v_lshl_add_u32 v10, v10, 9, v134
	v_lshl_add_u32 v11, v11, 9, v134
	v_lshl_add_u32 v12, v12, 9, v134
	v_lshl_add_u32 v13, v13, 9, v134
	v_lshl_add_u32 v14, v14, 9, v134
	v_lshl_add_u32 v15, v15, 9, v134
	s_waitcnt lgkmcnt(0)
	v_lshl_add_u32 v53, v53, 7, v54
	global_store_dword v254, v53, s[38:39] offset:48
	ds_read_b32 v0, v0 offset:32768
	ds_read_b32 v1, v1 offset:32768
	ds_read_b32 v2, v2 offset:32768
	ds_read_b32 v3, v3 offset:32768
	ds_read_b32 v4, v4 offset:32768
	ds_read_b32 v5, v5 offset:32768
	ds_read_b32 v6, v6 offset:32768
	ds_read_b32 v7, v7 offset:32768
	ds_read_b32 v8, v8 offset:32768
	ds_read_b32 v9, v9 offset:32768
	ds_read_b32 v10, v10 offset:32768
	ds_read_b32 v11, v11 offset:32768
	ds_read_b32 v12, v12 offset:32768
	ds_read_b32 v13, v13 offset:32768
	ds_read_b32 v14, v14 offset:32768
	ds_read_b32 v15, v15 offset:32768
	s_waitcnt lgkmcnt(0)
	v_add_f32_e32 v0, v32, v0
	v_add_f32_e32 v1, v33, v1
	v_add_f32_e32 v2, v34, v2
	v_add_f32_e32 v3, v35, v3
	v_add_f32_e32 v4, v36, v4
	v_add_f32_e32 v5, v37, v5
	v_add_f32_e32 v6, v38, v6
	v_add_f32_e32 v7, v39, v7
	v_add_f32_e32 v8, v40, v8
	v_add_f32_e32 v9, v41, v9
	v_add_f32_e32 v10, v42, v10
	v_add_f32_e32 v11, v43, v11
	v_add_f32_e32 v12, v44, v12
	v_add_f32_e32 v13, v45, v13
	v_add_f32_e32 v14, v46, v14
	v_add_f32_e32 v15, v47, v15
	v_cmp_gt_f32_e32 vcc, v1, v0
	v_cmp_gt_f32_e64 s[8:9], v3, v2
	v_cmp_gt_f32_e64 s[98:99], v5, v4
	v_cmp_gt_f32_e64 s[100:101], v7, v6
	v_cndmask_b32_e64 v0, v0, v1, vcc
	v_cndmask_b32_e64 v1, 0, 1, vcc
	v_cndmask_b32_e64 v2, v2, v3, s[8:9]
	v_cndmask_b32_e64 v3, 2, 3, s[8:9]
	v_cndmask_b32_e64 v4, v4, v5, s[98:99]
	v_cndmask_b32_e64 v5, 4, 5, s[98:99]
	v_cndmask_b32_e64 v6, v6, v7, s[100:101]
	v_cndmask_b32_e64 v7, 6, 7, s[100:101]
	v_cmp_gt_f32_e32 vcc, v9, v8
	v_cmp_gt_f32_e64 s[8:9], v11, v10
	v_cmp_gt_f32_e64 s[98:99], v13, v12
	v_cmp_gt_f32_e64 s[100:101], v15, v14
	v_cndmask_b32_e64 v8, v8, v9, vcc
	v_cndmask_b32_e64 v9, 8, 9, vcc
	v_cndmask_b32_e64 v10, v10, v11, s[8:9]
	v_cndmask_b32_e64 v11, 10, 11, s[8:9]
	v_cndmask_b32_e64 v12, v12, v13, s[98:99]
	v_cndmask_b32_e64 v13, 12, 13, s[98:99]
	v_cndmask_b32_e64 v14, v14, v15, s[100:101]
	v_cndmask_b32_e64 v15, 14, 15, s[100:101]
	v_cmp_gt_f32_e32 vcc, v2, v0
	v_cmp_gt_f32_e64 s[8:9], v6, v4
	v_cmp_gt_f32_e64 s[98:99], v10, v8
	v_cmp_gt_f32_e64 s[100:101], v14, v12
	v_cndmask_b32_e64 v0, v0, v2, vcc
	v_cndmask_b32_e64 v1, v1, v3, vcc
	v_cndmask_b32_e64 v4, v4, v6, s[8:9]
	v_cndmask_b32_e64 v5, v5, v7, s[8:9]
	v_cndmask_b32_e64 v8, v8, v10, s[98:99]
	v_cndmask_b32_e64 v9, v9, v11, s[98:99]
	v_cndmask_b32_e64 v12, v12, v14, s[100:101]
	v_cndmask_b32_e64 v13, v13, v15, s[100:101]
	v_cmp_gt_f32_e32 vcc, v4, v0
	v_cmp_gt_f32_e64 s[8:9], v12, v8
	s_nop 0
	v_cndmask_b32_e64 v0, v0, v4, vcc
	v_cndmask_b32_e64 v1, v1, v5, vcc
	v_cndmask_b32_e64 v8, v8, v12, s[8:9]
	v_cndmask_b32_e64 v9, v9, v13, s[8:9]
	v_cmp_gt_f32_e32 vcc, v8, v0
	s_nop 1
	v_cndmask_b32_e64 v0, v0, v8, vcc
	v_cndmask_b32_e64 v1, v1, v9, vcc
	v_sub_f32_e32 v29, v0, v255
	v_mul_f32_e32 v29, 0x3fb8aa3b, v29
	v_exp_f32_e32 v29, v29
	v_lshlrev_b32_e32 v50, 2, v1
	v_lshrrev_b64 v[52:53], v50, v[48:49]
	v_lshl_add_u32 v51, v1, 7, v135
	v_and_b32_e32 v52, 15, v52
	v_lshl_add_u32 v52, v52, 7, v206
	ds_read_u8 v53, v51
	ds_read_u8 v54, v52 offset:40960
	v_lshlrev_b64 v[50:51], v50, 1
	v_lshl_add_u64 v[48:49], v[50:51], 0, v[48:49]
	v_bfe_u32 v0, v48, 0, 4
	v_bfe_u32 v1, v48, 4, 4
	v_bfe_u32 v2, v48, 8, 4
	v_bfe_u32 v3, v48, 12, 4
	v_bfe_u32 v4, v48, 16, 4
	v_bfe_u32 v5, v48, 20, 4
	v_bfe_u32 v6, v48, 24, 4
	v_bfe_u32 v7, v48, 28, 4
	v_bfe_u32 v8, v49, 0, 4
	v_bfe_u32 v9, v49, 4, 4
	v_bfe_u32 v10, v49, 8, 4
	v_bfe_u32 v11, v49, 12, 4
	v_bfe_u32 v12, v49, 16, 4
	v_bfe_u32 v13, v49, 20, 4
	v_bfe_u32 v14, v49, 24, 4
	v_bfe_u32 v15, v49, 28, 4
	v_lshl_add_u32 v0, v0, 9, v134
	v_lshl_add_u32 v1, v1, 9, v134
	v_lshl_add_u32 v2, v2, 9, v134
	v_lshl_add_u32 v3, v3, 9, v134
	v_lshl_add_u32 v4, v4, 9, v134
	v_lshl_add_u32 v5, v5, 9, v134
	v_lshl_add_u32 v6, v6, 9, v134
	v_lshl_add_u32 v7, v7, 9, v134
	v_lshl_add_u32 v8, v8, 9, v134
	v_lshl_add_u32 v9, v9, 9, v134
	v_lshl_add_u32 v10, v10, 9, v134
	v_lshl_add_u32 v11, v11, 9, v134
	v_lshl_add_u32 v12, v12, 9, v134
	v_lshl_add_u32 v13, v13, 9, v134
	v_lshl_add_u32 v14, v14, 9, v134
	v_lshl_add_u32 v15, v15, 9, v134
	s_waitcnt lgkmcnt(0)
	v_lshl_add_u32 v53, v53, 7, v54
	global_store_dword v254, v53, s[38:39] offset:52
	ds_read_b32 v0, v0 offset:32768
	ds_read_b32 v1, v1 offset:32768
	ds_read_b32 v2, v2 offset:32768
	ds_read_b32 v3, v3 offset:32768
	ds_read_b32 v4, v4 offset:32768
	ds_read_b32 v5, v5 offset:32768
	ds_read_b32 v6, v6 offset:32768
	ds_read_b32 v7, v7 offset:32768
	ds_read_b32 v8, v8 offset:32768
	ds_read_b32 v9, v9 offset:32768
	ds_read_b32 v10, v10 offset:32768
	ds_read_b32 v11, v11 offset:32768
	ds_read_b32 v12, v12 offset:32768
	ds_read_b32 v13, v13 offset:32768
	ds_read_b32 v14, v14 offset:32768
	ds_read_b32 v15, v15 offset:32768
	s_waitcnt lgkmcnt(0)
	v_add_f32_e32 v0, v32, v0
	v_add_f32_e32 v1, v33, v1
	v_add_f32_e32 v2, v34, v2
	v_add_f32_e32 v3, v35, v3
	v_add_f32_e32 v4, v36, v4
	v_add_f32_e32 v5, v37, v5
	v_add_f32_e32 v6, v38, v6
	v_add_f32_e32 v7, v39, v7
	v_add_f32_e32 v8, v40, v8
	v_add_f32_e32 v9, v41, v9
	v_add_f32_e32 v10, v42, v10
	v_add_f32_e32 v11, v43, v11
	v_add_f32_e32 v12, v44, v12
	v_add_f32_e32 v13, v45, v13
	v_add_f32_e32 v14, v46, v14
	v_add_f32_e32 v15, v47, v15
	v_cmp_gt_f32_e32 vcc, v1, v0
	v_cmp_gt_f32_e64 s[8:9], v3, v2
	v_cmp_gt_f32_e64 s[98:99], v5, v4
	v_cmp_gt_f32_e64 s[100:101], v7, v6
	v_cndmask_b32_e64 v0, v0, v1, vcc
	v_cndmask_b32_e64 v1, 0, 1, vcc
	v_cndmask_b32_e64 v2, v2, v3, s[8:9]
	v_cndmask_b32_e64 v3, 2, 3, s[8:9]
	v_cndmask_b32_e64 v4, v4, v5, s[98:99]
	v_cndmask_b32_e64 v5, 4, 5, s[98:99]
	v_cndmask_b32_e64 v6, v6, v7, s[100:101]
	v_cndmask_b32_e64 v7, 6, 7, s[100:101]
	v_cmp_gt_f32_e32 vcc, v9, v8
	v_cmp_gt_f32_e64 s[8:9], v11, v10
	v_cmp_gt_f32_e64 s[98:99], v13, v12
	v_cmp_gt_f32_e64 s[100:101], v15, v14
	v_cndmask_b32_e64 v8, v8, v9, vcc
	v_cndmask_b32_e64 v9, 8, 9, vcc
	v_cndmask_b32_e64 v10, v10, v11, s[8:9]
	v_cndmask_b32_e64 v11, 10, 11, s[8:9]
	v_cndmask_b32_e64 v12, v12, v13, s[98:99]
	v_cndmask_b32_e64 v13, 12, 13, s[98:99]
	v_cndmask_b32_e64 v14, v14, v15, s[100:101]
	v_cndmask_b32_e64 v15, 14, 15, s[100:101]
	v_cmp_gt_f32_e32 vcc, v2, v0
	v_cmp_gt_f32_e64 s[8:9], v6, v4
	v_cmp_gt_f32_e64 s[98:99], v10, v8
	v_cmp_gt_f32_e64 s[100:101], v14, v12
	v_cndmask_b32_e64 v0, v0, v2, vcc
	v_cndmask_b32_e64 v1, v1, v3, vcc
	v_cndmask_b32_e64 v4, v4, v6, s[8:9]
	v_cndmask_b32_e64 v5, v5, v7, s[8:9]
	v_cndmask_b32_e64 v8, v8, v10, s[98:99]
	v_cndmask_b32_e64 v9, v9, v11, s[98:99]
	v_cndmask_b32_e64 v12, v12, v14, s[100:101]
	v_cndmask_b32_e64 v13, v13, v15, s[100:101]
	v_cmp_gt_f32_e32 vcc, v4, v0
	v_cmp_gt_f32_e64 s[8:9], v12, v8
	s_nop 0
	v_cndmask_b32_e64 v0, v0, v4, vcc
	v_cndmask_b32_e64 v1, v1, v5, vcc
	v_cndmask_b32_e64 v8, v8, v12, s[8:9]
	v_cndmask_b32_e64 v9, v9, v13, s[8:9]
	v_cmp_gt_f32_e32 vcc, v8, v0
	s_nop 1
	v_cndmask_b32_e64 v0, v0, v8, vcc
	v_cndmask_b32_e64 v1, v1, v9, vcc
	v_sub_f32_e32 v30, v0, v255
	v_mul_f32_e32 v30, 0x3fb8aa3b, v30
	v_exp_f32_e32 v30, v30
	v_lshlrev_b32_e32 v50, 2, v1
	v_lshrrev_b64 v[52:53], v50, v[48:49]
	v_lshl_add_u32 v51, v1, 7, v135
	v_and_b32_e32 v52, 15, v52
	v_lshl_add_u32 v52, v52, 7, v206
	ds_read_u8 v53, v51
	ds_read_u8 v54, v52 offset:40960
	v_lshlrev_b64 v[50:51], v50, 1
	v_lshl_add_u64 v[48:49], v[50:51], 0, v[48:49]
	v_bfe_u32 v0, v48, 0, 4
	v_bfe_u32 v1, v48, 4, 4
	v_bfe_u32 v2, v48, 8, 4
	v_bfe_u32 v3, v48, 12, 4
	v_bfe_u32 v4, v48, 16, 4
	v_bfe_u32 v5, v48, 20, 4
	v_bfe_u32 v6, v48, 24, 4
	v_bfe_u32 v7, v48, 28, 4
	v_bfe_u32 v8, v49, 0, 4
	v_bfe_u32 v9, v49, 4, 4
	v_bfe_u32 v10, v49, 8, 4
	v_bfe_u32 v11, v49, 12, 4
	v_bfe_u32 v12, v49, 16, 4
	v_bfe_u32 v13, v49, 20, 4
	v_bfe_u32 v14, v49, 24, 4
	v_bfe_u32 v15, v49, 28, 4
	v_lshl_add_u32 v0, v0, 9, v134
	v_lshl_add_u32 v1, v1, 9, v134
	v_lshl_add_u32 v2, v2, 9, v134
	v_lshl_add_u32 v3, v3, 9, v134
	v_lshl_add_u32 v4, v4, 9, v134
	v_lshl_add_u32 v5, v5, 9, v134
	v_lshl_add_u32 v6, v6, 9, v134
	v_lshl_add_u32 v7, v7, 9, v134
	v_lshl_add_u32 v8, v8, 9, v134
	v_lshl_add_u32 v9, v9, 9, v134
	v_lshl_add_u32 v10, v10, 9, v134
	v_lshl_add_u32 v11, v11, 9, v134
	v_lshl_add_u32 v12, v12, 9, v134
	v_lshl_add_u32 v13, v13, 9, v134
	v_lshl_add_u32 v14, v14, 9, v134
	v_lshl_add_u32 v15, v15, 9, v134
	s_waitcnt lgkmcnt(0)
	v_lshl_add_u32 v53, v53, 7, v54
	global_store_dword v254, v53, s[38:39] offset:56
	ds_read_b32 v0, v0 offset:32768
	ds_read_b32 v1, v1 offset:32768
	ds_read_b32 v2, v2 offset:32768
	ds_read_b32 v3, v3 offset:32768
	ds_read_b32 v4, v4 offset:32768
	ds_read_b32 v5, v5 offset:32768
	ds_read_b32 v6, v6 offset:32768
	ds_read_b32 v7, v7 offset:32768
	ds_read_b32 v8, v8 offset:32768
	ds_read_b32 v9, v9 offset:32768
	ds_read_b32 v10, v10 offset:32768
	ds_read_b32 v11, v11 offset:32768
	ds_read_b32 v12, v12 offset:32768
	ds_read_b32 v13, v13 offset:32768
	ds_read_b32 v14, v14 offset:32768
	ds_read_b32 v15, v15 offset:32768
	s_waitcnt lgkmcnt(0)
	v_add_f32_e32 v0, v32, v0
	v_add_f32_e32 v1, v33, v1
	v_add_f32_e32 v2, v34, v2
	v_add_f32_e32 v3, v35, v3
	v_add_f32_e32 v4, v36, v4
	v_add_f32_e32 v5, v37, v5
	v_add_f32_e32 v6, v38, v6
	v_add_f32_e32 v7, v39, v7
	v_add_f32_e32 v8, v40, v8
	v_add_f32_e32 v9, v41, v9
	v_add_f32_e32 v10, v42, v10
	v_add_f32_e32 v11, v43, v11
	v_add_f32_e32 v12, v44, v12
	v_add_f32_e32 v13, v45, v13
	v_add_f32_e32 v14, v46, v14
	v_add_f32_e32 v15, v47, v15
	v_cmp_gt_f32_e32 vcc, v1, v0
	v_cmp_gt_f32_e64 s[8:9], v3, v2
	v_cmp_gt_f32_e64 s[98:99], v5, v4
	v_cmp_gt_f32_e64 s[100:101], v7, v6
	v_cndmask_b32_e64 v0, v0, v1, vcc
	v_cndmask_b32_e64 v1, 0, 1, vcc
	v_cndmask_b32_e64 v2, v2, v3, s[8:9]
	v_cndmask_b32_e64 v3, 2, 3, s[8:9]
	v_cndmask_b32_e64 v4, v4, v5, s[98:99]
	v_cndmask_b32_e64 v5, 4, 5, s[98:99]
	v_cndmask_b32_e64 v6, v6, v7, s[100:101]
	v_cndmask_b32_e64 v7, 6, 7, s[100:101]
	v_cmp_gt_f32_e32 vcc, v9, v8
	v_cmp_gt_f32_e64 s[8:9], v11, v10
	v_cmp_gt_f32_e64 s[98:99], v13, v12
	v_cmp_gt_f32_e64 s[100:101], v15, v14
	v_cndmask_b32_e64 v8, v8, v9, vcc
	v_cndmask_b32_e64 v9, 8, 9, vcc
	v_cndmask_b32_e64 v10, v10, v11, s[8:9]
	v_cndmask_b32_e64 v11, 10, 11, s[8:9]
	v_cndmask_b32_e64 v12, v12, v13, s[98:99]
	v_cndmask_b32_e64 v13, 12, 13, s[98:99]
	v_cndmask_b32_e64 v14, v14, v15, s[100:101]
	v_cndmask_b32_e64 v15, 14, 15, s[100:101]
	v_cmp_gt_f32_e32 vcc, v2, v0
	v_cmp_gt_f32_e64 s[8:9], v6, v4
	v_cmp_gt_f32_e64 s[98:99], v10, v8
	v_cmp_gt_f32_e64 s[100:101], v14, v12
	v_cndmask_b32_e64 v0, v0, v2, vcc
	v_cndmask_b32_e64 v1, v1, v3, vcc
	v_cndmask_b32_e64 v4, v4, v6, s[8:9]
	v_cndmask_b32_e64 v5, v5, v7, s[8:9]
	v_cndmask_b32_e64 v8, v8, v10, s[98:99]
	v_cndmask_b32_e64 v9, v9, v11, s[98:99]
	v_cndmask_b32_e64 v12, v12, v14, s[100:101]
	v_cndmask_b32_e64 v13, v13, v15, s[100:101]
	v_cmp_gt_f32_e32 vcc, v4, v0
	v_cmp_gt_f32_e64 s[8:9], v12, v8
	s_nop 0
	v_cndmask_b32_e64 v0, v0, v4, vcc
	v_cndmask_b32_e64 v1, v1, v5, vcc
	v_cndmask_b32_e64 v8, v8, v12, s[8:9]
	v_cndmask_b32_e64 v9, v9, v13, s[8:9]
	v_cmp_gt_f32_e32 vcc, v8, v0
	s_nop 1
	v_cndmask_b32_e64 v0, v0, v8, vcc
	v_cndmask_b32_e64 v1, v1, v9, vcc
	v_sub_f32_e32 v31, v0, v255
	v_mul_f32_e32 v31, 0x3fb8aa3b, v31
	v_exp_f32_e32 v31, v31
	v_lshlrev_b32_e32 v50, 2, v1
	v_lshrrev_b64 v[52:53], v50, v[48:49]
	v_lshl_add_u32 v51, v1, 7, v135
	v_and_b32_e32 v52, 15, v52
	v_lshl_add_u32 v52, v52, 7, v206
	ds_read_u8 v53, v51
	ds_read_u8 v54, v52 offset:40960
	v_lshlrev_b64 v[50:51], v50, 1
	v_lshl_add_u64 v[48:49], v[50:51], 0, v[48:49]
	s_waitcnt lgkmcnt(0)
	v_lshl_add_u32 v53, v53, 7, v54
	global_store_dword v254, v53, s[38:39] offset:60
	v_add_f32_e32 v32, 0, v16
	v_add_f32_e32 v32, v32, v17
	v_add_f32_e32 v32, v32, v18
	v_add_f32_e32 v32, v32, v19
	v_add_f32_e32 v32, v32, v20
	v_add_f32_e32 v32, v32, v21
	v_add_f32_e32 v32, v32, v22
	v_add_f32_e32 v32, v32, v23
	v_add_f32_e32 v32, v32, v24
	v_add_f32_e32 v32, v32, v25
	v_add_f32_e32 v32, v32, v26
	v_add_f32_e32 v32, v32, v27
	v_add_f32_e32 v32, v32, v28
	v_add_f32_e32 v32, v32, v29
	v_add_f32_e32 v32, v32, v30
	v_add_f32_e32 v32, v32, v31
	v_div_scale_f32 v33, s[8:9], v32, v32, 1.0
	v_rcp_f32_e32 v34, v33
	s_nop 0
	v_fma_f32 v35, -v33, v34, 1.0
	v_fmac_f32_e32 v34, v35, v34
	v_div_scale_f32 v35, vcc, 1.0, v32, 1.0
	v_mul_f32_e32 v36, v35, v34
	v_fma_f32 v37, -v33, v36, v35
	v_fmac_f32_e32 v36, v37, v34
	v_fma_f32 v33, -v33, v36, v35
	s_nop 1
	v_div_fmas_f32 v33, v33, v34, v36
	v_div_fixup_f32 v32, v33, v32, 1.0
	v_mul_f32_e32 v16, v16, v32
	v_mul_f32_e32 v17, v17, v32
	v_mul_f32_e32 v18, v18, v32
	v_mul_f32_e32 v19, v19, v32
	v_mul_f32_e32 v20, v20, v32
	v_mul_f32_e32 v21, v21, v32
	v_mul_f32_e32 v22, v22, v32
	v_mul_f32_e32 v23, v23, v32
	v_mul_f32_e32 v24, v24, v32
	v_mul_f32_e32 v25, v25, v32
	v_mul_f32_e32 v26, v26, v32
	v_mul_f32_e32 v27, v27, v32
	v_mul_f32_e32 v28, v28, v32
	v_mul_f32_e32 v29, v29, v32
	v_mul_f32_e32 v30, v30, v32
	v_mul_f32_e32 v31, v31, v32
	global_store_dwordx4 v254, v[16:19], s[36:37] offset:0
	global_store_dwordx4 v254, v[20:23], s[36:37] offset:16
	global_store_dwordx4 v254, v[24:27], s[36:37] offset:32
	global_store_dwordx4 v254, v[28:31], s[36:37] offset:48
	s_branch .LBB0_619
